# RG-LRU carry pass too: channel-owning waves with resident W_r/W_i fragments (no per-item W loads) in both LRU phases
# speedup vs baseline: 1.0774x; 1.0207x over previous
; template <bool FINAL>
; __device__ void phase_lru(const Params& p, int l, unsigned char* smem) {
;     ...
;   const int tid = TIDX(), lane = tid & 63, w = tid >> 6, l15 = lane & 15, g = lane >> 4;
;   const int e_ = tid & 63, qd = tid >> 6;
;   const int NIT = NCHUNK * 8;
;   const int step = gridDim.x;
;   int it = BIDX();
;   uint4 x0 = make_uint4(0, 0, 0, 0), x1 = x0, x2 = x0;
;   auto load_x = [&](int item, uint4& a0, uint4& a1, uint4& a2) {
;     const int ci = item >> 3, nb = item & 7;
;     const int tb = ci * 64, pos0 = tok_pos(tb), S = tok_len(tb);
;     const u16* zb = p.Z + (long)(tb - 2) * DIN + C_LX + nb * 64;
;     { int idx = tid, r = idx >> 3, ch = idx & 7, pp = pos0 - 2 + r;
;       a0 = (pp >= 0 && pp < S) ? *(const uint4*)(zb + (long)r * DIN + ch * 8) : make_uint4(0, 0, 0, 0); }
;     { int idx = tid + 256, r = idx >> 3, ch = idx & 7, pp = pos0 - 2 + r;
;       a1 = (pp >= 0 && pp < S) ? *(const uint4*)(zb + (long)r * DIN + ch * 8) : make_uint4(0, 0, 0, 0); }
;     { int idx = tid + 512, r = idx >> 3, ch = idx & 7, pp = pos0 - 2 + r;
;       a2 = (idx < 67 * 8 && pp >= 0 && pp < S) ? *(const uint4*)(zb + (long)r * DIN + ch * 8) : make_uint4(0, 0, 0, 0); }
;   };
;   if (it < NIT) load_x(it, x0, x1, x2);
;     ...
;         uf[0] = *(const bf16x8*)(ub + (16 * w + l15) * 72 + g * 8);
;         uf[1] = *(const bf16x8*)(ub + (16 * w + l15) * 72 + 32 + g * 8);
;         const int t = 16 * w + l15;
; #pragma unroll
;         for (int et = 0; et < 4; ++et) {
;           f32x4 ar = {0.f, 0.f, 0.f, 0.f}, ai = {0.f, 0.f, 0.f, 0.f};
;           const u16* wr = p.WLRU + ((((size_t)(l * 2 + d) * 2 + 0) * 8 + nb) * 64 + et * 16 + l15) * 64 + g * 8;
;           const u16* wi = p.WLRU + ((((size_t)(l * 2 + d) * 2 + 1) * 8 + nb) * 64 + et * 16 + l15) * 64 + g * 8;
; #pragma unroll
;           for (int ks = 0; ks < 2; ++ks) {
;             ar = mfma16(*(const bf16x8*)(wr + ks * 32), uf[ks], ar);
;             ai = mfma16(*(const bf16x8*)(wi + ks * 32), uf[ks], ai);
;           }
;           const int e0 = et * 16 + 4 * g, ch0 = nb * 64 + e0;
;           const float4 ba4 = *(const float4*)(p.ba + (l * 2 + d) * 512 + ch0);
;           const float4 bx4 = *(const float4*)(p.bx + (l * 2 + d) * 512 + ch0);
;           const float4 sp4 = *(const float4*)(p.SP8 + (l * 2 + d) * 512 + ch0);
;           const float4 uu = *(const float4*)(u32 + t * 64 + e0);
.LBB0_373:
	s_or_b64 exec, exec, s[40:41]
	v_and_b32_e32 v59, 63, v45
	v_and_b32_e32 v12, 0x7fffffc0, v12
	v_ashrrev_i32_e32 v13, 6, v45
	v_lshlrev_b32_e32 v16, 1, v59
	v_lshlrev_b32_e32 v12, 1, v12
	v_lshlrev_b32_e32 v18, 1, v144
	v_and_b32_e32 v60, 15, v45
	v_add_u32_e32 v17, 0, v16
	v_add3_u32 v61, 0, v12, v18
	v_lshlrev_b32_e32 v18, 4, v13
	v_add_u32_e32 v62, v17, v16
	v_or_b32_e32 v16, v18, v60
	v_mul_lo_u32 v19, v16, s28
	v_and_b32_e32 v20, 48, v45
	v_bfe_u32 v14, v45, 4, 2
	v_add3_u32 v46, 0, v19, v20
	v_and_b32_e32 v19, 0x3fffffc0, v45
	s_lshl_b32 s36, s72, 6
	s_and_b32 s30, 0xffff, s42
	v_lshlrev_b32_e32 v44, 3, v14
	v_lshlrev_b32_e32 v63, 2, v14
	v_lshlrev_b32_e32 v14, 2, v45
	v_readlane_b32 s4, v248, 16
	v_lshlrev_b32_e32 v19, 2, v19
	v_lshlrev_b32_e32 v20, 2, v59
	s_cmp_lg_u32 s30, 0
	v_add_u32_e32 v64, s4, v14
	v_add3_u32 v65, s4, v19, v20
	s_movk_i32 s4, 0x70
	s_cselect_b64 s[42:43], -1, 0
	v_mad_u64_u32 v[48:49], s[46:47], v16, s4, v[46:47]
	v_readlane_b32 s4, v248, 17
	s_cmp_lg_u64 s[42:43], 0
	v_mad_i64_i32 v[40:41], s[30:31], v47, s26, 0
	v_mad_i64_i32 v[42:43], s[30:31], v57, s26, 0
	v_add_u32_e32 v97, s4, v14
	v_readlane_b32 s4, v248, 18
	s_addc_u32 s62, s58, 0
	s_lshl_b32 s30, s22, 1
	v_add_u32_e32 v98, s4, v14
	v_readlane_b32 s4, v248, 19
	s_or_b32 s50, s30, 1
	s_ashr_i32 s31, s30, 31
	v_add_u32_e32 v99, s4, v14
	v_readlane_b32 s4, v248, 20
	s_lshl_b32 s44, s22, 10
	s_lshl_b32 s52, s50, 9
	v_add_u32_e32 v100, s4, v14
	v_readlane_b32 s4, v250, 5
	s_lshl_b32 s63, s22, 11
	s_lshl_b32 s64, s22, 9
	s_ashr_i32 s45, s44, 31
	s_ashr_i32 s51, s50, 31
	s_ashr_i32 s53, s52, 31
	s_lshl_b64 s[30:31], s[30:31], 17
	v_readlane_b32 s10, v250, 11
	v_or_b32_e32 v18, 1, v18
	v_readlane_b32 s11, v250, 12
	v_readlane_b32 s16, v250, 17
	v_readlane_b32 s17, v250, 18
	v_readlane_b32 s18, v250, 19
	v_readlane_b32 s19, v250, 20
	s_add_u32 s94, s10, s30
	v_lshlrev_b32_e32 v12, 11, v13
	v_lshlrev_b32_e32 v66, 12, v13
	v_mul_lo_u32 v13, v13, s27
	v_lshlrev_b32_e32 v67, 8, v18
	v_mul_lo_u32 v18, v18, s28
	s_mov_b32 s98, s22
	s_addc_u32 s95, s11, s31
	v_readlane_b32 s16, v250, 37
	s_lshl_b64 s[48:49], s[44:45], 2
	v_readlane_b32 s24, v250, 45
	v_readlane_b32 s25, v250, 46
	s_add_u32 s44, s24, s48
	v_readlane_b32 s28, v250, 49
	s_addc_u32 s45, s25, s49
	v_or_b32_e32 v16, v66, v20
	v_readlane_b32 s29, v250, 50
	s_add_u32 s46, s28, s48
	v_or_b32_e32 v68, 0x200, v66
	v_add_u32_e32 v49, 0, v16
	v_or_b32_e32 v16, v67, v20
	v_readlane_b32 s14, v250, 15
	s_addc_u32 s47, s29, s49
	v_or_b32_e32 v69, 0x300, v66
	v_add_u32_e32 v82, 0, v16
	v_or_b32_e32 v16, v68, v20
	v_readlane_b32 s15, v250, 16
	s_add_u32 s48, s14, s48
	v_or_b32_e32 v70, 0x400, v66
	v_add_u32_e32 v83, 0, v16
	v_or_b32_e32 v16, v69, v20
	s_addc_u32 s49, s15, s49
	s_lshl_b64 s[50:51], s[50:51], 17
	v_or_b32_e32 v71, 0x500, v66
	v_add_u32_e32 v84, 0, v16
	v_or_b32_e32 v16, v70, v20
	s_add_u32 s50, s10, s50
	v_or_b32_e32 v72, 0x600, v66
	v_add_u32_e32 v85, 0, v16
	v_or_b32_e32 v16, v71, v20
	s_addc_u32 s51, s11, s51
	s_lshl_b64 s[56:57], s[52:53], 2
	v_or_b32_e32 v73, 0x700, v66
	v_add_u32_e32 v86, 0, v16
	v_or_b32_e32 v16, v72, v20
	s_add_u32 s52, s24, s56
	v_or_b32_e32 v74, 0x800, v66
	v_add_u32_e32 v87, 0, v16
	v_or_b32_e32 v16, v73, v20
	s_addc_u32 s53, s25, s57
	v_or_b32_e32 v75, 0x900, v66
	v_add_u32_e32 v88, 0, v16
	v_or_b32_e32 v16, v74, v20
	s_add_u32 s54, s28, s56
	v_or_b32_e32 v76, 0xa00, v66
	v_add_u32_e32 v89, 0, v16
	v_or_b32_e32 v16, v75, v20
	s_addc_u32 s55, s29, s57
	v_or_b32_e32 v77, 0xb00, v66
	v_add_u32_e32 v90, 0, v16
	v_or_b32_e32 v16, v76, v20
	s_add_u32 s56, s14, s56
	v_or_b32_e32 v78, 0xc00, v66
	v_add_u32_e32 v91, 0, v16
	v_or_b32_e32 v16, v77, v20
	s_addc_u32 s57, s15, s57
	s_lshl_b32 s65, s62, 6
	v_or_b32_e32 v79, 0xd00, v66
	v_add_u32_e32 v92, 0, v16
	v_or_b32_e32 v16, v78, v20
	s_cmp_lg_u64 s[42:43], 0
	v_cndmask_b32_e64 v15, 0, 1, s[42:43]
	v_or_b32_e32 v80, 0xe00, v66
	v_add_u32_e32 v93, 0, v16
	v_or_b32_e32 v16, v79, v20
	s_addc_u32 s42, s72, s58
	v_or_b32_e32 v81, 0xf00, v66
	v_add_u32_e32 v94, 0, v16
	v_or_b32_e32 v16, v80, v20
	s_lshl_b32 s66, s42, 3
	v_readfirstlane_b32 s42, v15
	v_add_u32_e32 v95, 0, v16
	v_or_b32_e32 v16, v81, v20
	s_lshl_b32 s68, s58, 6
	s_lshl_b32 s42, s42, 6
	v_cmp_gt_u32_e64 s[40:41], 64, v45
	v_add_u32_e32 v96, 0, v16
	s_lshl_b32 s67, s62, 3
	s_add_i32 s68, s68, s42
	v_add_u32_e32 v101, v17, v12
	v_add_u32_e32 v102, v17, v13
	v_add_u32_e32 v103, v17, v18
	v_readlane_b32 s5, v250, 6
	v_readlane_b32 s6, v250, 7
	v_readlane_b32 s7, v250, 8
	v_readlane_b32 s8, v250, 9
	v_readlane_b32 s9, v250, 10
	v_readlane_b32 s12, v250, 13
	v_readlane_b32 s13, v250, 14
	v_readlane_b32 s17, v250, 38
	v_readlane_b32 s18, v250, 39
	v_readlane_b32 s19, v250, 40
	v_readlane_b32 s20, v250, 41
	v_readlane_b32 s21, v250, 42
	v_readlane_b32 s22, v250, 43
	v_readlane_b32 s23, v250, 44
	v_readlane_b32 s26, v250, 47
	v_readlane_b32 s27, v250, 48
	v_readlane_b32 s30, v250, 51
	v_readlane_b32 s31, v250, 52
	s_and_b32 s32, s36, 0x1c0
	v_lshrrev_b32_e32 v12, 6, v147
	v_and_b32_e32 v22, 15, v147
	v_lshlrev_b32_e32 v13, 4, v12
	v_or_b32_e32 v13, v13, v22
	v_or_b32_e32 v13, s32, v13
	v_lshlrev_b32_e32 v14, 7, v13
	v_mov_b32_e32 v15, v145
	v_bfe_u32 v16, v147, 4, 2
	v_lshlrev_b32_e32 v17, 4, v16
	v_add_u32_e32 v14, v14, v17
	v_lshl_add_u64 v[18:19], s[94:95], 0, v[14:15]
	global_load_dwordx4 v[180:183], v[18:19], off
	global_load_dwordx4 v[184:187], v[18:19], off offset:64
	v_add_co_u32_e32 v20, vcc, 0x10000, v18
	s_nop 0
	v_addc_co_u32_e32 v21, vcc, 0, v19, vcc
	global_load_dwordx4 v[188:191], v[20:21], off
	global_load_dwordx4 v[192:195], v[20:21], off offset:64
	v_lshl_add_u64 v[18:19], s[50:51], 0, v[14:15]
	global_load_dwordx4 v[232:235], v[18:19], off
	global_load_dwordx4 v[236:239], v[18:19], off offset:64
	v_add_co_u32_e32 v20, vcc, 0x10000, v18
	s_nop 0
	v_addc_co_u32_e32 v21, vcc, 0, v19, vcc
	global_load_dwordx4 v[240:243], v[20:21], off
	global_load_dwordx4 v[244:247], v[20:21], off offset:64
	v_mul_u32_u24_e32 v229, 0x90, v22
	v_add_u32_e32 v229, v229, v17
	v_lshlrev_b32_e32 v230, 8, v22
	v_add_u32_e32 v230, v230, v17
	v_lshl_add_u32 v230, v12, 6, v230
	v_lshlrev_b32_e32 v231, 4, v12
	v_lshl_add_u32 v231, v16, 2, v231
	v_or_b32_e32 v231, s32, v231
	v_lshlrev_b32_e32 v231, 2, v231
	s_branch .LBB0_375

; __device__ __forceinline__ float bf2f(unsigned h) { return __uint_as_float(h << 16); }
; template <bool FINAL>
; __device__ void phase_lru(const Params& p, int l, unsigned char* smem) {
;     ...
;     {
;       const int ch = nb * 64 + e_;
;       const float cw0 = p.conv_w[(l * 4 + 0) * 512 + ch], cw1 = p.conv_w[(l * 4 + 1) * 512 + ch],
;                   cw2 = p.conv_w[(l * 4 + 2) * 512 + ch], cw3 = p.conv_w[(l * 4 + 3) * 512 + ch];
;       const float cb = p.conv_b[l * 512 + ch];
;       float xv[19];
; #pragma unroll
;       for (int k = 0; k < 19; ++k) xv[k] = bf2f(xs[(qd * 16 + k) * 64 + e_]);
; #pragma unroll
;       for (int tt = 0; tt < 16; ++tt) {
;         const int t = qd * 16 + tt;
;         const float u = cb + xv[tt] * cw0 + xv[tt + 1] * cw1 + xv[tt + 2] * cw2 + xv[tt + 3] * cw3;
;         u32[t * 64 + e_] = u;
;         ub[t * 72 + e_] = (u16)f2bf(u);
;       }
;     }
.LBB0_385:
	s_and_b32 s60, s36, 0x1c0
	v_or_b32_e32 v18, s60, v59
	v_or_b32_e32 v12, s63, v18
	v_readlane_b32 s4, v250, 37
	v_ashrrev_i32_e32 v13, 31, v12
	v_readlane_b32 s6, v250, 39
	v_readlane_b32 s7, v250, 40
	v_readlane_b32 s8, v250, 41
	v_readlane_b32 s9, v250, 42
	v_lshl_add_u64 v[14:15], v[12:13], 2, s[6:7]
	v_add_co_u32_e32 v16, vcc, 0x1000, v14
	global_load_dword v13, v[14:15], off
	global_load_dword v12, v[14:15], off offset:2048
	v_addc_co_u32_e32 v17, vcc, 0, v15, vcc
	global_load_dword v15, v[16:17], off
	global_load_dword v14, v[16:17], off offset:2048
	v_or_b32_e32 v16, s64, v18
	v_ashrrev_i32_e32 v17, 31, v16
	v_lshl_add_u64 v[16:17], v[16:17], 2, s[8:9]
	global_load_dword v16, v[16:17], off
	ds_read_u16 v17, v101
	ds_read_u16 v18, v101 offset:128
	ds_read_u16 v19, v101 offset:256
	ds_read_u16 v20, v101 offset:384
	ds_read_u16 v21, v101 offset:512
	ds_read_u16 v22, v101 offset:640
	ds_read_u16 v23, v101 offset:768
	ds_read_u16 v24, v101 offset:896
	s_waitcnt lgkmcnt(7)
	v_lshlrev_b32_e32 v17, 16, v17
	s_waitcnt lgkmcnt(6)
	v_lshlrev_b32_e32 v18, 16, v18
	s_waitcnt lgkmcnt(5)
	v_lshlrev_b32_e32 v19, 16, v19
	s_waitcnt lgkmcnt(4)
	v_lshlrev_b32_e32 v20, 16, v20
	v_add_u32_e32 v50, v62, v66
	ds_read_u16 v25, v101 offset:1024
	ds_read_u16 v26, v101 offset:1152
	ds_read_u16 v27, v101 offset:1280
	ds_read_u16 v28, v101 offset:1408
	ds_read_u16 v29, v101 offset:1536
	ds_read_u16 v30, v101 offset:1664
	ds_read_u16 v31, v101 offset:1792
	ds_read_u16 v32, v101 offset:1920
	ds_read_u16 v33, v101 offset:2048
	ds_read_u16 v34, v101 offset:2176
	ds_read_u16 v35, v101 offset:2304
	s_waitcnt lgkmcnt(14)
	v_lshlrev_b32_e32 v21, 16, v21
	s_waitcnt lgkmcnt(13)
	v_lshlrev_b32_e32 v22, 16, v22
	s_waitcnt lgkmcnt(12)
	v_lshlrev_b32_e32 v23, 16, v23
	s_waitcnt lgkmcnt(11)
	v_lshlrev_b32_e32 v24, 16, v24
	s_waitcnt lgkmcnt(10)
	v_lshlrev_b32_e32 v25, 16, v25
	s_waitcnt lgkmcnt(9)
	v_lshlrev_b32_e32 v26, 16, v26
	s_waitcnt lgkmcnt(8)
	v_lshlrev_b32_e32 v27, 16, v27
	s_waitcnt lgkmcnt(7)
	v_lshlrev_b32_e32 v28, 16, v28
	s_waitcnt lgkmcnt(6)
	v_lshlrev_b32_e32 v29, 16, v29
	s_waitcnt lgkmcnt(5)
	v_lshlrev_b32_e32 v30, 16, v30
	s_waitcnt lgkmcnt(4)
	v_lshlrev_b32_e32 v31, 16, v31
	s_waitcnt lgkmcnt(3)
	v_lshlrev_b32_e32 v32, 16, v32
	s_waitcnt lgkmcnt(2)
	v_lshlrev_b32_e32 v33, 16, v33
	s_ashr_i32 s42, s72, 3
	s_ashr_i32 s43, s42, 31
	s_waitcnt lgkmcnt(1)
	v_lshlrev_b32_e32 v34, 16, v34
	s_lshl_b64 s[42:43], s[42:43], 10
	v_add_u32_e32 v144, s60, v45
	s_waitcnt lgkmcnt(0)
	v_lshlrev_b32_e32 v35, 16, v35
	v_lshlrev_b32_e32 v54, 1, v44
	v_mov_b32_e32 v55, v145
	v_readlane_b32 s5, v250, 38
	s_mov_b64 s[4:5], 0x10000
	v_or_b32_e32 v56, s60, v63
	v_lshlrev_b32_e32 v104, 2, v56
	s_mov_b32 s6, 0xbe800000
	s_mov_b64 s[8:9], 0x10800
	v_readlane_b32 s10, v250, 43
	v_readlane_b32 s11, v250, 44
	v_readlane_b32 s12, v250, 45
	v_readlane_b32 s13, v250, 46
	v_readlane_b32 s14, v250, 47
	v_readlane_b32 s15, v250, 48
	v_readlane_b32 s16, v250, 49
	v_readlane_b32 s17, v250, 50
	v_readlane_b32 s18, v250, 51
	v_readlane_b32 s19, v250, 52
	s_waitcnt vmcnt(0)
	v_fma_f32 v17, v13, v17, v16
	v_fmac_f32_e32 v17, v12, v18
	v_fmac_f32_e32 v17, v15, v19
	v_fmac_f32_e32 v17, v14, v20
	ds_write_b32 v50, v17 offset:8704
	v_cvt_pk_bf16_f32 v17, v17, s0
	ds_write_b16 v102, v17 offset:25088
	v_fma_f32 v17, v13, v18, v16
	v_fmac_f32_e32 v17, v12, v19
	v_fmac_f32_e32 v17, v15, v20
	v_fmac_f32_e32 v17, v14, v21
	v_add_u32_e32 v18, v62, v67
	ds_write_b32 v18, v17 offset:8704
	v_cvt_pk_bf16_f32 v17, v17, s0
	ds_write_b16 v103, v17 offset:25088
	v_fma_f32 v17, v13, v19, v16
	v_fmac_f32_e32 v17, v12, v20
	v_fmac_f32_e32 v17, v15, v21
	v_fmac_f32_e32 v17, v14, v22
	v_add_u32_e32 v18, v62, v68
	ds_write_b32 v18, v17 offset:8704
	v_cvt_pk_bf16_f32 v17, v17, s0
	ds_write_b16 v103, v17 offset:25232
	v_fma_f32 v17, v13, v20, v16
	v_fmac_f32_e32 v17, v12, v21
	v_fmac_f32_e32 v17, v15, v22
	v_fmac_f32_e32 v17, v14, v23
	v_add_u32_e32 v18, v62, v69
	ds_write_b32 v18, v17 offset:8704
	v_cvt_pk_bf16_f32 v17, v17, s0
	ds_write_b16 v103, v17 offset:25376
	v_fma_f32 v17, v13, v21, v16
	v_fmac_f32_e32 v17, v12, v22
	v_fmac_f32_e32 v17, v15, v23
	v_fmac_f32_e32 v17, v14, v24
	v_add_u32_e32 v18, v62, v70
	ds_write_b32 v18, v17 offset:8704
	v_cvt_pk_bf16_f32 v17, v17, s0
	ds_write_b16 v103, v17 offset:25520
	v_fma_f32 v17, v13, v22, v16
	v_fmac_f32_e32 v17, v12, v23
	v_fmac_f32_e32 v17, v15, v24
	v_fmac_f32_e32 v17, v14, v25
	v_add_u32_e32 v18, v62, v71
	ds_write_b32 v18, v17 offset:8704
	v_cvt_pk_bf16_f32 v17, v17, s0
	ds_write_b16 v103, v17 offset:25664
	v_fma_f32 v17, v13, v23, v16
	v_fmac_f32_e32 v17, v12, v24
	v_fmac_f32_e32 v17, v15, v25
	v_fmac_f32_e32 v17, v14, v26
	v_add_u32_e32 v18, v62, v72
	ds_write_b32 v18, v17 offset:8704
	v_cvt_pk_bf16_f32 v17, v17, s0
	ds_write_b16 v103, v17 offset:25808
	v_fma_f32 v17, v13, v24, v16
	v_fmac_f32_e32 v17, v12, v25
	v_fmac_f32_e32 v17, v15, v26
	v_fmac_f32_e32 v17, v14, v27
	v_add_u32_e32 v18, v62, v73
	ds_write_b32 v18, v17 offset:8704
	v_cvt_pk_bf16_f32 v17, v17, s0
	ds_write_b16 v103, v17 offset:25952
	v_fma_f32 v17, v13, v25, v16
	v_fmac_f32_e32 v17, v12, v26
	v_fmac_f32_e32 v17, v15, v27
	v_fmac_f32_e32 v17, v14, v28
	v_add_u32_e32 v18, v62, v74
	ds_write_b32 v18, v17 offset:8704
	v_cvt_pk_bf16_f32 v17, v17, s0
	ds_write_b16 v103, v17 offset:26096
	v_fma_f32 v17, v13, v26, v16
	v_fmac_f32_e32 v17, v12, v27
	v_fmac_f32_e32 v17, v15, v28
	v_fmac_f32_e32 v17, v14, v29
	v_add_u32_e32 v18, v62, v75
	ds_write_b32 v18, v17 offset:8704
	v_cvt_pk_bf16_f32 v17, v17, s0
	ds_write_b16 v103, v17 offset:26240
	v_fma_f32 v17, v13, v27, v16
	v_fmac_f32_e32 v17, v12, v28
; template <bool FINAL>
; __device__ void phase_lru(const Params& p, int l, unsigned char* smem) {
;     ...
;       for (int tt = 0; tt < 16; ++tt) {
;         const int t = qd * 16 + tt;
;         const float u = cb + xv[tt] * cw0 + xv[tt + 1] * cw1 + xv[tt + 2] * cw2 + xv[tt + 3] * cw3;
;         u32[t * 64 + e_] = u;
;         ub[t * 72 + e_] = (u16)f2bf(u);
;       }
;     }
;     ...
;       {
;         bf16x8 uf[2];
;         uf[0] = *(const bf16x8*)(ub + (16 * w + l15) * 72 + g * 8);
;         uf[1] = *(const bf16x8*)(ub + (16 * w + l15) * 72 + 32 + g * 8);
;         const int t = 16 * w + l15;
; #pragma unroll
;         for (int et = 0; et < 4; ++et) {
;           f32x4 ar = {0.f, 0.f, 0.f, 0.f}, ai = {0.f, 0.f, 0.f, 0.f};
;           const u16* wr = p.WLRU + ((((size_t)(l * 2 + d) * 2 + 0) * 8 + nb) * 64 + et * 16 + l15) * 64 + g * 8;
;           const u16* wi = p.WLRU + ((((size_t)(l * 2 + d) * 2 + 1) * 8 + nb) * 64 + et * 16 + l15) * 64 + g * 8;
; #pragma unroll
;           for (int ks = 0; ks < 2; ++ks) {
;             ar = mfma16(*(const bf16x8*)(wr + ks * 32), uf[ks], ar);
;             ai = mfma16(*(const bf16x8*)(wi + ks * 32), uf[ks], ai);
;           }
;           const int e0 = et * 16 + 4 * g, ch0 = nb * 64 + e0;
;           const float4 ba4 = *(const float4*)(p.ba + (l * 2 + d) * 512 + ch0);
;           const float4 bx4 = *(const float4*)(p.bx + (l * 2 + d) * 512 + ch0);
;           const float4 sp4 = *(const float4*)(p.SP8 + (l * 2 + d) * 512 + ch0);
;           const float4 uu = *(const float4*)(u32 + t * 64 + e0);
;           const float* bap = (const float*)&ba4; const float* bxp = (const float*)&bx4;
;           const float* spp = (const float*)&sp4; const float* uup = (const float*)&uu;
;           f32x4 av, bv;
; #pragma unroll
;           for (int j = 0; j < 4; ++j) {
;             float r = sigmoidf_(ar[j] + bap[j]);
;             float ig = sigmoidf_(ai[j] + bxp[j]);
;             float la = spp[j] * r;
;             float av_ = __expf(la);
;             float t2 = 2.0f * la;
;             float ser = -t2 * (1.f + t2 * 0.5f * (1.f + t2 * (1.f / 3.f) * (1.f + t2 * 0.25f * (1.f + t2 * 0.2f))));
;             float om = (t2 > -0.25f) ? ser : (1.0f - av_ * av_);
;             av[j] = av_;
;             bv[j] = __builtin_amdgcn_sqrtf(om) * ig * uup[j];
;           }
;           *(f32x4*)(sa + t * 64 + e0) = av;
	v_fmac_f32_e32 v17, v15, v29
	v_fmac_f32_e32 v17, v14, v30
	v_add_u32_e32 v18, v62, v76
	ds_write_b32 v18, v17 offset:8704
	v_cvt_pk_bf16_f32 v17, v17, s0
	ds_write_b16 v103, v17 offset:26384
	v_fma_f32 v17, v13, v28, v16
	v_fmac_f32_e32 v17, v12, v29
	v_fmac_f32_e32 v17, v15, v30
	v_fmac_f32_e32 v17, v14, v31
	v_add_u32_e32 v18, v62, v77
	ds_write_b32 v18, v17 offset:8704
	v_cvt_pk_bf16_f32 v17, v17, s0
	ds_write_b16 v103, v17 offset:26528
	v_fma_f32 v17, v13, v29, v16
	v_fmac_f32_e32 v17, v12, v30
	v_fmac_f32_e32 v17, v15, v31
	v_fmac_f32_e32 v17, v14, v32
	v_add_u32_e32 v18, v62, v78
	ds_write_b32 v18, v17 offset:8704
	v_cvt_pk_bf16_f32 v17, v17, s0
	ds_write_b16 v103, v17 offset:26672
	v_fma_f32 v17, v13, v30, v16
	v_fmac_f32_e32 v17, v12, v31
	v_fmac_f32_e32 v17, v15, v32
	v_fmac_f32_e32 v17, v14, v33
	v_add_u32_e32 v18, v62, v79
	ds_write_b32 v18, v17 offset:8704
	v_cvt_pk_bf16_f32 v17, v17, s0
	ds_write_b16 v103, v17 offset:26816
	v_fma_f32 v17, v13, v31, v16
	v_fmac_f32_e32 v16, v13, v32
	v_fmac_f32_e32 v17, v12, v32
	v_fmac_f32_e32 v16, v12, v33
	v_or_b32_e32 v20, s60, v60
	v_fmac_f32_e32 v17, v15, v33
	v_fmac_f32_e32 v16, v15, v34
	v_lshl_add_u64 v[50:51], v[144:145], 0, s[42:43]
	v_lshlrev_b32_e32 v144, 7, v20
	v_fmac_f32_e32 v17, v14, v34
	v_add_u32_e32 v18, v62, v80
	v_fmac_f32_e32 v16, v14, v35
	v_add_u32_e32 v12, v62, v81
	v_lshl_add_u64 v[20:21], s[94:95], 0, v[144:145]
	ds_write_b32 v18, v17 offset:8704
	v_cvt_pk_bf16_f32 v17, v17, s0
	ds_write_b32 v12, v16 offset:8704
	v_cvt_pk_bf16_f32 v12, v16, s0
	v_lshl_add_u64 v[28:29], v[20:21], 0, v[54:55]
	ds_write_b16 v103, v17 offset:26960
	ds_write_b16 v103, v12 offset:27104
	s_waitcnt lgkmcnt(0)
	s_barrier
	s_mov_b32 s5, 0x3e4ccccd
	global_load_dwordx4 v[196:199], v231, s[44:45]
	global_load_dwordx4 v[200:203], v231, s[46:47]
	global_load_dwordx4 v[32:35], v231, s[48:49]
	ds_read_b128 v[12:15], v229 offset:25088
	ds_read_b128 v[16:19], v229 offset:25152
	ds_read_b128 v[28:31], v230 offset:8704
	s_waitcnt lgkmcnt(1)
	v_mfma_f32_16x16x32_bf16 v[20:23], v[180:183], v[12:15], 0
	v_mfma_f32_16x16x32_bf16 v[24:27], v[188:191], v[12:15], 0
	v_mfma_f32_16x16x32_bf16 v[20:23], v[184:187], v[16:19], v[20:23]
	v_mfma_f32_16x16x32_bf16 v[24:27], v[192:195], v[16:19], v[24:27]
	s_waitcnt vmcnt(0)
	s_nop 7
	s_nop 3
	s_waitcnt lgkmcnt(0)
	v_add_f32_e32 v20, v20, v196
	v_add_f32_e32 v21, v21, v197
	v_add_f32_e32 v24, v24, v200
	v_add_f32_e32 v25, v25, v201
	v_mul_f32_e32 v20, 0xbfb8aa3b, v20
	v_mul_f32_e32 v21, 0xbfb8aa3b, v21
	v_mul_f32_e32 v24, 0xbfb8aa3b, v24
	v_mul_f32_e32 v25, 0xbfb8aa3b, v25
	v_exp_f32_e32 v20, v20
	v_exp_f32_e32 v21, v21
	v_exp_f32_e32 v24, v24
	v_exp_f32_e32 v25, v25
	v_add_f32_e32 v20, 1.0, v20
	v_add_f32_e32 v21, 1.0, v21
	v_add_f32_e32 v24, 1.0, v24
	v_add_f32_e32 v25, 1.0, v25
	v_rcp_f32_e32 v20, v20
	v_rcp_f32_e32 v21, v21
	v_rcp_f32_e32 v24, v24
	v_rcp_f32_e32 v25, v25
	v_pk_mul_f32 v[12:13], v[20:21], v[32:33]
	s_nop 0
	v_pk_add_f32 v[14:15], v[12:13], v[12:13]
	v_mul_f32_e32 v20, 0x3fb8aa3b, v12
	v_mul_f32_e32 v21, 0x3fb8aa3b, v13
	v_exp_f32_e32 v20, v20
	v_exp_f32_e32 v21, v21
	v_mul_f32_e32 v16, 0x3e800000, v14
	v_fma_f32 v17, v14, s5, 1.0
	v_mul_f32_e32 v18, 0x3eaaaaab, v14
	v_fma_f32 v16, v16, v17, 1.0
	v_mul_f32_e32 v17, 0.5, v14
	v_fma_f32 v18, v18, v16, 1.0
	v_fma_f32 v17, v17, v18, 1.0
	v_mul_f32_e64 v17, v17, -v14
	v_fma_f32 v16, -v20, v20, 1.0
	v_cmp_lt_f32_e32 vcc, s6, v14
	v_mul_f32_e32 v19, 0x3e800000, v15
	v_fma_f32 v12, v15, s5, 1.0
	v_cndmask_b32_e32 v16, v16, v17, vcc
	v_mul_f32_e32 v13, 0x3eaaaaab, v15
	v_fma_f32 v19, v19, v12, 1.0
	v_mul_f32_e32 v12, 0.5, v15
	v_fma_f32 v13, v13, v19, 1.0
	v_fma_f32 v12, v12, v13, 1.0
	v_mul_f32_e64 v12, v12, -v15
	v_fma_f32 v13, -v21, v21, 1.0
	v_cmp_lt_f32_e32 vcc, s6, v15
	v_sqrt_f32_e32 v16, v16
	s_nop 1
	v_cndmask_b32_e32 v17, v13, v12, vcc
	v_sqrt_f32_e32 v17, v17
	s_nop 0
	v_pk_mul_f32 v[24:25], v[24:25], v[16:17]
	s_nop 0
	v_pk_mul_f32 v[24:25], v[28:29], v[24:25]
	v_add_f32_e32 v22, v22, v198
	v_add_f32_e32 v23, v23, v199
	v_add_f32_e32 v26, v26, v202
	v_add_f32_e32 v27, v27, v203
	v_mul_f32_e32 v22, 0xbfb8aa3b, v22
	v_mul_f32_e32 v23, 0xbfb8aa3b, v23
	v_mul_f32_e32 v26, 0xbfb8aa3b, v26
	v_mul_f32_e32 v27, 0xbfb8aa3b, v27
	v_exp_f32_e32 v22, v22
	v_exp_f32_e32 v23, v23
	v_exp_f32_e32 v26, v26
	v_exp_f32_e32 v27, v27
	v_add_f32_e32 v22, 1.0, v22
	v_add_f32_e32 v23, 1.0, v23
	v_add_f32_e32 v26, 1.0, v26
	v_add_f32_e32 v27, 1.0, v27
	v_rcp_f32_e32 v22, v22
	v_rcp_f32_e32 v23, v23
	v_rcp_f32_e32 v26, v26
	v_rcp_f32_e32 v27, v27
	v_pk_mul_f32 v[12:13], v[22:23], v[34:35]
	s_nop 0
	v_pk_add_f32 v[14:15], v[12:13], v[12:13]
	v_mul_f32_e32 v22, 0x3fb8aa3b, v12
	v_mul_f32_e32 v23, 0x3fb8aa3b, v13
	v_exp_f32_e32 v22, v22
	v_exp_f32_e32 v23, v23
	v_mul_f32_e32 v16, 0x3e800000, v14
	v_fma_f32 v17, v14, s5, 1.0
	v_mul_f32_e32 v18, 0x3eaaaaab, v14
	v_fma_f32 v16, v16, v17, 1.0
	v_mul_f32_e32 v17, 0.5, v14
	v_fma_f32 v18, v18, v16, 1.0
	v_fma_f32 v17, v17, v18, 1.0
	v_mul_f32_e64 v17, v17, -v14
	v_fma_f32 v16, -v22, v22, 1.0
	v_cmp_lt_f32_e32 vcc, s6, v14
	v_mul_f32_e32 v19, 0x3e800000, v15
	v_fma_f32 v12, v15, s5, 1.0
	v_cndmask_b32_e32 v16, v16, v17, vcc
	v_mul_f32_e32 v13, 0x3eaaaaab, v15
	v_fma_f32 v19, v19, v12, 1.0
	v_mul_f32_e32 v12, 0.5, v15
	v_fma_f32 v13, v13, v19, 1.0
	v_fma_f32 v12, v12, v13, 1.0
	v_mul_f32_e64 v12, v12, -v15
	v_fma_f32 v13, -v23, v23, 1.0
	v_cmp_lt_f32_e32 vcc, s6, v15
	v_sqrt_f32_e32 v16, v16
	s_nop 1
	v_cndmask_b32_e32 v17, v13, v12, vcc
	v_sqrt_f32_e32 v17, v17
	s_nop 0
	v_pk_mul_f32 v[26:27], v[26:27], v[16:17]
	s_nop 0
	v_pk_mul_f32 v[26:27], v[30:31], v[26:27]
	ds_write_b128 v230, v[20:23] offset:34304
	ds_write_b128 v230, v[24:27] offset:50688
	ds_read_b128 v[12:15], v229 offset:27392
	ds_read_b128 v[16:19], v229 offset:27456
	ds_read_b128 v[28:31], v230 offset:12800
	s_waitcnt lgkmcnt(1)
; __device__ __forceinline__ float sigmoidf_(float x) { return __builtin_amdgcn_rcpf(1.0f + __expf(-x)); }
; template <bool FINAL>
; __device__ void phase_lru(const Params& p, int l, unsigned char* smem) {
;     ...
;       {
;         bf16x8 uf[2];
;         uf[0] = *(const bf16x8*)(ub + (16 * w + l15) * 72 + g * 8);
;         uf[1] = *(const bf16x8*)(ub + (16 * w + l15) * 72 + 32 + g * 8);
;         const int t = 16 * w + l15;
; #pragma unroll
;         for (int et = 0; et < 4; ++et) {
;           f32x4 ar = {0.f, 0.f, 0.f, 0.f}, ai = {0.f, 0.f, 0.f, 0.f};
;           const u16* wr = p.WLRU + ((((size_t)(l * 2 + d) * 2 + 0) * 8 + nb) * 64 + et * 16 + l15) * 64 + g * 8;
;           const u16* wi = p.WLRU + ((((size_t)(l * 2 + d) * 2 + 1) * 8 + nb) * 64 + et * 16 + l15) * 64 + g * 8;
; #pragma unroll
;           for (int ks = 0; ks < 2; ++ks) {
;             ar = mfma16(*(const bf16x8*)(wr + ks * 32), uf[ks], ar);
;             ai = mfma16(*(const bf16x8*)(wi + ks * 32), uf[ks], ai);
;           }
;           const int e0 = et * 16 + 4 * g, ch0 = nb * 64 + e0;
;           const float4 ba4 = *(const float4*)(p.ba + (l * 2 + d) * 512 + ch0);
;           const float4 bx4 = *(const float4*)(p.bx + (l * 2 + d) * 512 + ch0);
;           const float4 sp4 = *(const float4*)(p.SP8 + (l * 2 + d) * 512 + ch0);
;           const float4 uu = *(const float4*)(u32 + t * 64 + e0);
;           const float* bap = (const float*)&ba4; const float* bxp = (const float*)&bx4;
;           const float* spp = (const float*)&sp4; const float* uup = (const float*)&uu;
;           f32x4 av, bv;
; #pragma unroll
;           for (int j = 0; j < 4; ++j) {
;             float r = sigmoidf_(ar[j] + bap[j]);
;             float ig = sigmoidf_(ai[j] + bxp[j]);
;             float la = spp[j] * r;
;             float av_ = __expf(la);
;             float t2 = 2.0f * la;
;             float ser = -t2 * (1.f + t2 * 0.5f * (1.f + t2 * (1.f / 3.f) * (1.f + t2 * 0.25f * (1.f + t2 * 0.2f))));
;             float om = (t2 > -0.25f) ? ser : (1.0f - av_ * av_);
;             av[j] = av_;
;             bv[j] = __builtin_amdgcn_sqrtf(om) * ig * uup[j];
;           }
;           *(f32x4*)(sa + t * 64 + e0) = av;
;           *(f32x4*)(sb + t * 64 + e0) = bv;
;         }
;       }
	v_mfma_f32_16x16x32_bf16 v[20:23], v[180:183], v[12:15], 0
	v_mfma_f32_16x16x32_bf16 v[24:27], v[188:191], v[12:15], 0
	v_mfma_f32_16x16x32_bf16 v[20:23], v[184:187], v[16:19], v[20:23]
	v_mfma_f32_16x16x32_bf16 v[24:27], v[192:195], v[16:19], v[24:27]
	s_nop 7
	s_nop 3
	s_waitcnt lgkmcnt(0)
	v_add_f32_e32 v20, v20, v196
	v_add_f32_e32 v21, v21, v197
	v_add_f32_e32 v24, v24, v200
	v_add_f32_e32 v25, v25, v201
	v_mul_f32_e32 v20, 0xbfb8aa3b, v20
	v_mul_f32_e32 v21, 0xbfb8aa3b, v21
	v_mul_f32_e32 v24, 0xbfb8aa3b, v24
	v_mul_f32_e32 v25, 0xbfb8aa3b, v25
	v_exp_f32_e32 v20, v20
	v_exp_f32_e32 v21, v21
	v_exp_f32_e32 v24, v24
	v_exp_f32_e32 v25, v25
	v_add_f32_e32 v20, 1.0, v20
	v_add_f32_e32 v21, 1.0, v21
	v_add_f32_e32 v24, 1.0, v24
	v_add_f32_e32 v25, 1.0, v25
	v_rcp_f32_e32 v20, v20
	v_rcp_f32_e32 v21, v21
	v_rcp_f32_e32 v24, v24
	v_rcp_f32_e32 v25, v25
	v_pk_mul_f32 v[12:13], v[20:21], v[32:33]
	s_nop 0
	v_pk_add_f32 v[14:15], v[12:13], v[12:13]
	v_mul_f32_e32 v20, 0x3fb8aa3b, v12
	v_mul_f32_e32 v21, 0x3fb8aa3b, v13
	v_exp_f32_e32 v20, v20
	v_exp_f32_e32 v21, v21
	v_mul_f32_e32 v16, 0x3e800000, v14
	v_fma_f32 v17, v14, s5, 1.0
	v_mul_f32_e32 v18, 0x3eaaaaab, v14
	v_fma_f32 v16, v16, v17, 1.0
	v_mul_f32_e32 v17, 0.5, v14
	v_fma_f32 v18, v18, v16, 1.0
	v_fma_f32 v17, v17, v18, 1.0
	v_mul_f32_e64 v17, v17, -v14
	v_fma_f32 v16, -v20, v20, 1.0
	v_cmp_lt_f32_e32 vcc, s6, v14
	v_mul_f32_e32 v19, 0x3e800000, v15
	v_fma_f32 v12, v15, s5, 1.0
	v_cndmask_b32_e32 v16, v16, v17, vcc
	v_mul_f32_e32 v13, 0x3eaaaaab, v15
	v_fma_f32 v19, v19, v12, 1.0
	v_mul_f32_e32 v12, 0.5, v15
	v_fma_f32 v13, v13, v19, 1.0
	v_fma_f32 v12, v12, v13, 1.0
	v_mul_f32_e64 v12, v12, -v15
	v_fma_f32 v13, -v21, v21, 1.0
	v_cmp_lt_f32_e32 vcc, s6, v15
	v_sqrt_f32_e32 v16, v16
	s_nop 1
	v_cndmask_b32_e32 v17, v13, v12, vcc
	v_sqrt_f32_e32 v17, v17
	s_nop 0
	v_pk_mul_f32 v[24:25], v[24:25], v[16:17]
	s_nop 0
	v_pk_mul_f32 v[24:25], v[28:29], v[24:25]
	v_add_f32_e32 v22, v22, v198
	v_add_f32_e32 v23, v23, v199
	v_add_f32_e32 v26, v26, v202
	v_add_f32_e32 v27, v27, v203
	v_mul_f32_e32 v22, 0xbfb8aa3b, v22
	v_mul_f32_e32 v23, 0xbfb8aa3b, v23
	v_mul_f32_e32 v26, 0xbfb8aa3b, v26
	v_mul_f32_e32 v27, 0xbfb8aa3b, v27
	v_exp_f32_e32 v22, v22
	v_exp_f32_e32 v23, v23
	v_exp_f32_e32 v26, v26
	v_exp_f32_e32 v27, v27
	v_add_f32_e32 v22, 1.0, v22
	v_add_f32_e32 v23, 1.0, v23
	v_add_f32_e32 v26, 1.0, v26
	v_add_f32_e32 v27, 1.0, v27
	v_rcp_f32_e32 v22, v22
	v_rcp_f32_e32 v23, v23
	v_rcp_f32_e32 v26, v26
	v_rcp_f32_e32 v27, v27
	v_pk_mul_f32 v[12:13], v[22:23], v[34:35]
	s_nop 0
	v_pk_add_f32 v[14:15], v[12:13], v[12:13]
	v_mul_f32_e32 v22, 0x3fb8aa3b, v12
	v_mul_f32_e32 v23, 0x3fb8aa3b, v13
	v_exp_f32_e32 v22, v22
	v_exp_f32_e32 v23, v23
	v_mul_f32_e32 v16, 0x3e800000, v14
	v_fma_f32 v17, v14, s5, 1.0
	v_mul_f32_e32 v18, 0x3eaaaaab, v14
	v_fma_f32 v16, v16, v17, 1.0
	v_mul_f32_e32 v17, 0.5, v14
	v_fma_f32 v18, v18, v16, 1.0
	v_fma_f32 v17, v17, v18, 1.0
	v_mul_f32_e64 v17, v17, -v14
	v_fma_f32 v16, -v22, v22, 1.0
	v_cmp_lt_f32_e32 vcc, s6, v14
	v_mul_f32_e32 v19, 0x3e800000, v15
	v_fma_f32 v12, v15, s5, 1.0
	v_cndmask_b32_e32 v16, v16, v17, vcc
	v_mul_f32_e32 v13, 0x3eaaaaab, v15
	v_fma_f32 v19, v19, v12, 1.0
	v_mul_f32_e32 v12, 0.5, v15
	v_fma_f32 v13, v13, v19, 1.0
	v_fma_f32 v12, v12, v13, 1.0
	v_mul_f32_e64 v12, v12, -v15
	v_fma_f32 v13, -v23, v23, 1.0
	v_cmp_lt_f32_e32 vcc, s6, v15
	v_sqrt_f32_e32 v16, v16
	s_nop 1
	v_cndmask_b32_e32 v17, v13, v12, vcc
	v_sqrt_f32_e32 v17, v17
	s_nop 0
	v_pk_mul_f32 v[26:27], v[26:27], v[16:17]
	s_nop 0
	v_pk_mul_f32 v[26:27], v[30:31], v[26:27]
	ds_write_b128 v230, v[20:23] offset:38400
	ds_write_b128 v230, v[24:27] offset:54784
	ds_read_b128 v[12:15], v229 offset:29696
	ds_read_b128 v[16:19], v229 offset:29760
	ds_read_b128 v[28:31], v230 offset:16896
	s_waitcnt lgkmcnt(1)
	v_mfma_f32_16x16x32_bf16 v[20:23], v[180:183], v[12:15], 0
	v_mfma_f32_16x16x32_bf16 v[24:27], v[188:191], v[12:15], 0
	v_mfma_f32_16x16x32_bf16 v[20:23], v[184:187], v[16:19], v[20:23]
	v_mfma_f32_16x16x32_bf16 v[24:27], v[192:195], v[16:19], v[24:27]
	s_nop 7
	s_nop 3
	s_waitcnt lgkmcnt(0)
	v_add_f32_e32 v20, v20, v196
	v_add_f32_e32 v21, v21, v197
	v_add_f32_e32 v24, v24, v200
	v_add_f32_e32 v25, v25, v201
	v_mul_f32_e32 v20, 0xbfb8aa3b, v20
	v_mul_f32_e32 v21, 0xbfb8aa3b, v21
	v_mul_f32_e32 v24, 0xbfb8aa3b, v24
	v_mul_f32_e32 v25, 0xbfb8aa3b, v25
	v_exp_f32_e32 v20, v20
	v_exp_f32_e32 v21, v21
	v_exp_f32_e32 v24, v24
	v_exp_f32_e32 v25, v25
	v_add_f32_e32 v20, 1.0, v20
	v_add_f32_e32 v21, 1.0, v21
	v_add_f32_e32 v24, 1.0, v24
	v_add_f32_e32 v25, 1.0, v25
	v_rcp_f32_e32 v20, v20
	v_rcp_f32_e32 v21, v21
	v_rcp_f32_e32 v24, v24
	v_rcp_f32_e32 v25, v25
	v_pk_mul_f32 v[12:13], v[20:21], v[32:33]
	s_nop 0
	v_pk_add_f32 v[14:15], v[12:13], v[12:13]
	v_mul_f32_e32 v20, 0x3fb8aa3b, v12
	v_mul_f32_e32 v21, 0x3fb8aa3b, v13
	v_exp_f32_e32 v20, v20
	v_exp_f32_e32 v21, v21
	v_mul_f32_e32 v16, 0x3e800000, v14
	v_fma_f32 v17, v14, s5, 1.0
	v_mul_f32_e32 v18, 0x3eaaaaab, v14
	v_fma_f32 v16, v16, v17, 1.0
	v_mul_f32_e32 v17, 0.5, v14
	v_fma_f32 v18, v18, v16, 1.0
	v_fma_f32 v17, v17, v18, 1.0
	v_mul_f32_e64 v17, v17, -v14
	v_fma_f32 v16, -v20, v20, 1.0
	v_cmp_lt_f32_e32 vcc, s6, v14
	v_mul_f32_e32 v19, 0x3e800000, v15
	v_fma_f32 v12, v15, s5, 1.0
	v_cndmask_b32_e32 v16, v16, v17, vcc
	v_mul_f32_e32 v13, 0x3eaaaaab, v15
	v_fma_f32 v19, v19, v12, 1.0
	v_mul_f32_e32 v12, 0.5, v15
	v_fma_f32 v13, v13, v19, 1.0
	v_fma_f32 v12, v12, v13, 1.0
	v_mul_f32_e64 v12, v12, -v15
	v_fma_f32 v13, -v21, v21, 1.0
	v_cmp_lt_f32_e32 vcc, s6, v15
	v_sqrt_f32_e32 v16, v16
	s_nop 1
	v_cndmask_b32_e32 v17, v13, v12, vcc
; __device__ __forceinline__ float sigmoidf_(float x) { return __builtin_amdgcn_rcpf(1.0f + __expf(-x)); }
; template <bool FINAL>
; __device__ void phase_lru(const Params& p, int l, unsigned char* smem) {
;     ...
;       {
;         bf16x8 uf[2];
;         uf[0] = *(const bf16x8*)(ub + (16 * w + l15) * 72 + g * 8);
;         uf[1] = *(const bf16x8*)(ub + (16 * w + l15) * 72 + 32 + g * 8);
;         const int t = 16 * w + l15;
; #pragma unroll
;         for (int et = 0; et < 4; ++et) {
;           f32x4 ar = {0.f, 0.f, 0.f, 0.f}, ai = {0.f, 0.f, 0.f, 0.f};
;           const u16* wr = p.WLRU + ((((size_t)(l * 2 + d) * 2 + 0) * 8 + nb) * 64 + et * 16 + l15) * 64 + g * 8;
;           const u16* wi = p.WLRU + ((((size_t)(l * 2 + d) * 2 + 1) * 8 + nb) * 64 + et * 16 + l15) * 64 + g * 8;
; #pragma unroll
;           for (int ks = 0; ks < 2; ++ks) {
;             ar = mfma16(*(const bf16x8*)(wr + ks * 32), uf[ks], ar);
;             ai = mfma16(*(const bf16x8*)(wi + ks * 32), uf[ks], ai);
;           }
;           const int e0 = et * 16 + 4 * g, ch0 = nb * 64 + e0;
;           const float4 ba4 = *(const float4*)(p.ba + (l * 2 + d) * 512 + ch0);
;           const float4 bx4 = *(const float4*)(p.bx + (l * 2 + d) * 512 + ch0);
;           const float4 sp4 = *(const float4*)(p.SP8 + (l * 2 + d) * 512 + ch0);
;           const float4 uu = *(const float4*)(u32 + t * 64 + e0);
;           const float* bap = (const float*)&ba4; const float* bxp = (const float*)&bx4;
;           const float* spp = (const float*)&sp4; const float* uup = (const float*)&uu;
;           f32x4 av, bv;
; #pragma unroll
;           for (int j = 0; j < 4; ++j) {
;             float r = sigmoidf_(ar[j] + bap[j]);
;             float ig = sigmoidf_(ai[j] + bxp[j]);
;             float la = spp[j] * r;
;             float av_ = __expf(la);
;             float t2 = 2.0f * la;
;             float ser = -t2 * (1.f + t2 * 0.5f * (1.f + t2 * (1.f / 3.f) * (1.f + t2 * 0.25f * (1.f + t2 * 0.2f))));
;             float om = (t2 > -0.25f) ? ser : (1.0f - av_ * av_);
;             av[j] = av_;
;             bv[j] = __builtin_amdgcn_sqrtf(om) * ig * uup[j];
;           }
;           *(f32x4*)(sa + t * 64 + e0) = av;
;           *(f32x4*)(sb + t * 64 + e0) = bv;
;         }
;       }
;       __syncthreads();
	v_sqrt_f32_e32 v17, v17
	s_nop 0
	v_pk_mul_f32 v[24:25], v[24:25], v[16:17]
	s_nop 0
	v_pk_mul_f32 v[24:25], v[28:29], v[24:25]
	v_add_f32_e32 v22, v22, v198
	v_add_f32_e32 v23, v23, v199
	v_add_f32_e32 v26, v26, v202
	v_add_f32_e32 v27, v27, v203
	v_mul_f32_e32 v22, 0xbfb8aa3b, v22
	v_mul_f32_e32 v23, 0xbfb8aa3b, v23
	v_mul_f32_e32 v26, 0xbfb8aa3b, v26
	v_mul_f32_e32 v27, 0xbfb8aa3b, v27
	v_exp_f32_e32 v22, v22
	v_exp_f32_e32 v23, v23
	v_exp_f32_e32 v26, v26
	v_exp_f32_e32 v27, v27
	v_add_f32_e32 v22, 1.0, v22
	v_add_f32_e32 v23, 1.0, v23
	v_add_f32_e32 v26, 1.0, v26
	v_add_f32_e32 v27, 1.0, v27
	v_rcp_f32_e32 v22, v22
	v_rcp_f32_e32 v23, v23
	v_rcp_f32_e32 v26, v26
	v_rcp_f32_e32 v27, v27
	v_pk_mul_f32 v[12:13], v[22:23], v[34:35]
	s_nop 0
	v_pk_add_f32 v[14:15], v[12:13], v[12:13]
	v_mul_f32_e32 v22, 0x3fb8aa3b, v12
	v_mul_f32_e32 v23, 0x3fb8aa3b, v13
	v_exp_f32_e32 v22, v22
	v_exp_f32_e32 v23, v23
	v_mul_f32_e32 v16, 0x3e800000, v14
	v_fma_f32 v17, v14, s5, 1.0
	v_mul_f32_e32 v18, 0x3eaaaaab, v14
	v_fma_f32 v16, v16, v17, 1.0
	v_mul_f32_e32 v17, 0.5, v14
	v_fma_f32 v18, v18, v16, 1.0
	v_fma_f32 v17, v17, v18, 1.0
	v_mul_f32_e64 v17, v17, -v14
	v_fma_f32 v16, -v22, v22, 1.0
	v_cmp_lt_f32_e32 vcc, s6, v14
	v_mul_f32_e32 v19, 0x3e800000, v15
	v_fma_f32 v12, v15, s5, 1.0
	v_cndmask_b32_e32 v16, v16, v17, vcc
	v_mul_f32_e32 v13, 0x3eaaaaab, v15
	v_fma_f32 v19, v19, v12, 1.0
	v_mul_f32_e32 v12, 0.5, v15
	v_fma_f32 v13, v13, v19, 1.0
	v_fma_f32 v12, v12, v13, 1.0
	v_mul_f32_e64 v12, v12, -v15
	v_fma_f32 v13, -v23, v23, 1.0
	v_cmp_lt_f32_e32 vcc, s6, v15
	v_sqrt_f32_e32 v16, v16
	s_nop 1
	v_cndmask_b32_e32 v17, v13, v12, vcc
	v_sqrt_f32_e32 v17, v17
	s_nop 0
	v_pk_mul_f32 v[26:27], v[26:27], v[16:17]
	s_nop 0
	v_pk_mul_f32 v[26:27], v[30:31], v[26:27]
	ds_write_b128 v230, v[20:23] offset:42496
	ds_write_b128 v230, v[24:27] offset:58880
	ds_read_b128 v[12:15], v229 offset:32000
	ds_read_b128 v[16:19], v229 offset:32064
	ds_read_b128 v[28:31], v230 offset:20992
	s_waitcnt lgkmcnt(1)
	v_mfma_f32_16x16x32_bf16 v[20:23], v[180:183], v[12:15], 0
	v_mfma_f32_16x16x32_bf16 v[24:27], v[188:191], v[12:15], 0
	v_mfma_f32_16x16x32_bf16 v[20:23], v[184:187], v[16:19], v[20:23]
	v_mfma_f32_16x16x32_bf16 v[24:27], v[192:195], v[16:19], v[24:27]
	s_nop 7
	s_nop 3
	s_waitcnt lgkmcnt(0)
	v_add_f32_e32 v20, v20, v196
	v_add_f32_e32 v21, v21, v197
	v_add_f32_e32 v24, v24, v200
	v_add_f32_e32 v25, v25, v201
	v_mul_f32_e32 v20, 0xbfb8aa3b, v20
	v_mul_f32_e32 v21, 0xbfb8aa3b, v21
	v_mul_f32_e32 v24, 0xbfb8aa3b, v24
	v_mul_f32_e32 v25, 0xbfb8aa3b, v25
	v_exp_f32_e32 v20, v20
	v_exp_f32_e32 v21, v21
	v_exp_f32_e32 v24, v24
	v_exp_f32_e32 v25, v25
	v_add_f32_e32 v20, 1.0, v20
	v_add_f32_e32 v21, 1.0, v21
	v_add_f32_e32 v24, 1.0, v24
	v_add_f32_e32 v25, 1.0, v25
	v_rcp_f32_e32 v20, v20
	v_rcp_f32_e32 v21, v21
	v_rcp_f32_e32 v24, v24
	v_rcp_f32_e32 v25, v25
	v_pk_mul_f32 v[12:13], v[20:21], v[32:33]
	s_nop 0
	v_pk_add_f32 v[14:15], v[12:13], v[12:13]
	v_mul_f32_e32 v20, 0x3fb8aa3b, v12
	v_mul_f32_e32 v21, 0x3fb8aa3b, v13
	v_exp_f32_e32 v20, v20
	v_exp_f32_e32 v21, v21
	v_mul_f32_e32 v16, 0x3e800000, v14
	v_fma_f32 v17, v14, s5, 1.0
	v_mul_f32_e32 v18, 0x3eaaaaab, v14
	v_fma_f32 v16, v16, v17, 1.0
	v_mul_f32_e32 v17, 0.5, v14
	v_fma_f32 v18, v18, v16, 1.0
	v_fma_f32 v17, v17, v18, 1.0
	v_mul_f32_e64 v17, v17, -v14
	v_fma_f32 v16, -v20, v20, 1.0
	v_cmp_lt_f32_e32 vcc, s6, v14
	v_mul_f32_e32 v19, 0x3e800000, v15
	v_fma_f32 v12, v15, s5, 1.0
	v_cndmask_b32_e32 v16, v16, v17, vcc
	v_mul_f32_e32 v13, 0x3eaaaaab, v15
	v_fma_f32 v19, v19, v12, 1.0
	v_mul_f32_e32 v12, 0.5, v15
	v_fma_f32 v13, v13, v19, 1.0
	v_fma_f32 v12, v12, v13, 1.0
	v_mul_f32_e64 v12, v12, -v15
	v_fma_f32 v13, -v21, v21, 1.0
	v_cmp_lt_f32_e32 vcc, s6, v15
	v_sqrt_f32_e32 v16, v16
	s_nop 1
	v_cndmask_b32_e32 v17, v13, v12, vcc
	v_sqrt_f32_e32 v17, v17
	s_nop 0
	v_pk_mul_f32 v[24:25], v[24:25], v[16:17]
	s_nop 0
	v_pk_mul_f32 v[24:25], v[28:29], v[24:25]
	v_add_f32_e32 v22, v22, v198
	v_add_f32_e32 v23, v23, v199
	v_add_f32_e32 v26, v26, v202
	v_add_f32_e32 v27, v27, v203
	v_mul_f32_e32 v22, 0xbfb8aa3b, v22
	v_mul_f32_e32 v23, 0xbfb8aa3b, v23
	v_mul_f32_e32 v26, 0xbfb8aa3b, v26
	v_mul_f32_e32 v27, 0xbfb8aa3b, v27
	v_exp_f32_e32 v22, v22
	v_exp_f32_e32 v23, v23
	v_exp_f32_e32 v26, v26
	v_exp_f32_e32 v27, v27
	v_add_f32_e32 v22, 1.0, v22
	v_add_f32_e32 v23, 1.0, v23
	v_add_f32_e32 v26, 1.0, v26
	v_add_f32_e32 v27, 1.0, v27
	v_rcp_f32_e32 v22, v22
	v_rcp_f32_e32 v23, v23
	v_rcp_f32_e32 v26, v26
	v_rcp_f32_e32 v27, v27
	v_pk_mul_f32 v[12:13], v[22:23], v[34:35]
	s_nop 0
	v_pk_add_f32 v[14:15], v[12:13], v[12:13]
	v_mul_f32_e32 v22, 0x3fb8aa3b, v12
	v_mul_f32_e32 v23, 0x3fb8aa3b, v13
	v_exp_f32_e32 v22, v22
	v_exp_f32_e32 v23, v23
	v_mul_f32_e32 v16, 0x3e800000, v14
	v_fma_f32 v17, v14, s5, 1.0
	v_mul_f32_e32 v18, 0x3eaaaaab, v14
	v_fma_f32 v16, v16, v17, 1.0
	v_mul_f32_e32 v17, 0.5, v14
	v_fma_f32 v18, v18, v16, 1.0
	v_fma_f32 v17, v17, v18, 1.0
	v_mul_f32_e64 v17, v17, -v14
	v_fma_f32 v16, -v22, v22, 1.0
	v_cmp_lt_f32_e32 vcc, s6, v14
	v_mul_f32_e32 v19, 0x3e800000, v15
	v_fma_f32 v12, v15, s5, 1.0
	v_cndmask_b32_e32 v16, v16, v17, vcc
	v_mul_f32_e32 v13, 0x3eaaaaab, v15
	v_fma_f32 v19, v19, v12, 1.0
	v_mul_f32_e32 v12, 0.5, v15
	v_fma_f32 v13, v13, v19, 1.0
	v_fma_f32 v12, v12, v13, 1.0
	v_mul_f32_e64 v12, v12, -v15
	v_fma_f32 v13, -v23, v23, 1.0
	v_cmp_lt_f32_e32 vcc, s6, v15
	v_sqrt_f32_e32 v16, v16
	s_nop 1
	v_cndmask_b32_e32 v17, v13, v12, vcc
	v_sqrt_f32_e32 v17, v17
	s_nop 0
	v_pk_mul_f32 v[26:27], v[26:27], v[16:17]
	s_nop 0
	v_pk_mul_f32 v[26:27], v[30:31], v[26:27]
	ds_write_b128 v230, v[20:23] offset:46592
	ds_write_b128 v230, v[24:27] offset:62976
	s_waitcnt lgkmcnt(0)
	s_barrier
; template <bool FINAL>
; __device__ void phase_lru(const Params& p, int l, unsigned char* smem) {
;     ...
;       {
;         bf16x8 uf[2];
;         uf[0] = *(const bf16x8*)(ub + (16 * w + l15) * 72 + g * 8);
;         uf[1] = *(const bf16x8*)(ub + (16 * w + l15) * 72 + 32 + g * 8);
;         const int t = 16 * w + l15;
; #pragma unroll
;         for (int et = 0; et < 4; ++et) {
;           f32x4 ar = {0.f, 0.f, 0.f, 0.f}, ai = {0.f, 0.f, 0.f, 0.f};
;           const u16* wr = p.WLRU + ((((size_t)(l * 2 + d) * 2 + 0) * 8 + nb) * 64 + et * 16 + l15) * 64 + g * 8;
;           const u16* wi = p.WLRU + ((((size_t)(l * 2 + d) * 2 + 1) * 8 + nb) * 64 + et * 16 + l15) * 64 + g * 8;
; #pragma unroll
;           for (int ks = 0; ks < 2; ++ks) {
;             ar = mfma16(*(const bf16x8*)(wr + ks * 32), uf[ks], ar);
;             ai = mfma16(*(const bf16x8*)(wi + ks * 32), uf[ks], ai);
;           }
;           const int e0 = et * 16 + 4 * g, ch0 = nb * 64 + e0;
;           const float4 ba4 = *(const float4*)(p.ba + (l * 2 + d) * 512 + ch0);
;           const float4 bx4 = *(const float4*)(p.bx + (l * 2 + d) * 512 + ch0);
;           const float4 sp4 = *(const float4*)(p.SP8 + (l * 2 + d) * 512 + ch0);
;           const float4 uu = *(const float4*)(u32 + t * 64 + e0);
;     ...
;       {
;         float A = 1.f, B = 0.f;
;         if (d == 0) {
; #pragma unroll
;           for (int tt = 0; tt < 16; ++tt) { int t = qd * 16 + tt; float a = sa[t * 64 + e_], b = sb[t * 64 + e_]; B = a * B + b; A *= a; }
;         } else {
; #pragma unroll
;     ...
;         }
;         part[(0 * 4 + qd) * 64 + e_] = A;
;         part[(1 * 4 + qd) * 64 + e_] = B;
;       }
;       __syncthreads();
;       if (!FINAL) {
;         if (qd == 0) {
;           float A = 1.f, B = 0.f;
;           if (d == 0) {
; #pragma unroll
;             for (int q = 0; q < 4; ++q) { float aq = part[q * 64 + e_], bq = part[(4 + q) * 64 + e_]; B = aq * B + bq; A *= aq; }
;           } else {
; #pragma unroll
;             for (int q = 3; q >= 0; --q) { float aq = part[q * 64 + e_], bq = part[(4 + q) * 64 + e_]; B = aq * B + bq; A *= aq; }
;           }
;           const size_t cidx = ((size_t)ci * 2 + d) * 512 + nb * 64 + e_;
;           p.CA[cidx] = A; p.CB[cidx] = B;
;         }
	ds_read2st64_b32 v[12:13], v49 offset0:134 offset1:198
	ds_read2st64_b32 v[14:15], v82 offset0:134 offset1:198
	ds_read2st64_b32 v[16:17], v83 offset0:134 offset1:198
	s_waitcnt lgkmcnt(2)
	v_fmac_f32_e32 v13, 0, v12
	s_waitcnt lgkmcnt(1)
	v_mul_f32_e32 v18, v12, v14
	s_waitcnt lgkmcnt(0)
	v_mul_f32_e32 v20, v18, v16
	ds_read2st64_b32 v[18:19], v84 offset0:134 offset1:198
	v_fmac_f32_e32 v15, v14, v13
	v_fmac_f32_e32 v17, v16, v15
	v_lshlrev_b64 v[12:13], 2, v[50:51]
	v_lshl_add_u64 v[50:51], s[86:87], 0, v[12:13]
	s_waitcnt lgkmcnt(0)
	v_mul_f32_e32 v22, v20, v18
	ds_read2st64_b32 v[20:21], v85 offset0:134 offset1:198
	v_fmac_f32_e32 v19, v18, v17
	s_waitcnt lgkmcnt(0)
	v_mul_f32_e32 v24, v22, v20
	ds_read2st64_b32 v[22:23], v86 offset0:134 offset1:198
	v_fmac_f32_e32 v21, v20, v19
	s_waitcnt lgkmcnt(0)
	v_mul_f32_e32 v26, v24, v22
	ds_read2st64_b32 v[24:25], v87 offset0:134 offset1:198
	v_fmac_f32_e32 v23, v22, v21
	s_waitcnt lgkmcnt(0)
	v_mul_f32_e32 v28, v26, v24
	ds_read2st64_b32 v[26:27], v88 offset0:134 offset1:198
	v_fmac_f32_e32 v25, v24, v23
	s_waitcnt lgkmcnt(0)
	v_mul_f32_e32 v30, v28, v26
	ds_read2st64_b32 v[28:29], v89 offset0:134 offset1:198
	v_fmac_f32_e32 v27, v26, v25
	s_waitcnt lgkmcnt(0)
	v_mul_f32_e32 v32, v30, v28
	ds_read2st64_b32 v[30:31], v90 offset0:134 offset1:198
	v_fmac_f32_e32 v29, v28, v27
	s_waitcnt lgkmcnt(0)
	v_mul_f32_e32 v34, v32, v30
	ds_read2st64_b32 v[32:33], v91 offset0:134 offset1:198
	v_fmac_f32_e32 v31, v30, v29
	s_waitcnt lgkmcnt(0)
	v_mul_f32_e32 v52, v34, v32
	ds_read2st64_b32 v[34:35], v92 offset0:134 offset1:198
	v_fmac_f32_e32 v33, v32, v31
	s_waitcnt lgkmcnt(0)
	v_mul_f32_e32 v104, v52, v34
	ds_read2st64_b32 v[52:53], v93 offset0:134 offset1:198
	v_fmac_f32_e32 v35, v34, v33
	s_waitcnt lgkmcnt(0)
	v_mul_f32_e32 v106, v104, v52
	ds_read2st64_b32 v[104:105], v94 offset0:134 offset1:198
	v_fmac_f32_e32 v53, v52, v35
	s_waitcnt lgkmcnt(0)
	v_mul_f32_e32 v108, v106, v104
	ds_read2st64_b32 v[106:107], v95 offset0:134 offset1:198
	v_fmac_f32_e32 v105, v104, v53
	v_lshl_add_u64 v[52:53], s[88:89], 0, v[12:13]
	s_waitcnt lgkmcnt(0)
	v_mul_f32_e32 v110, v108, v106
	ds_read2st64_b32 v[108:109], v96 offset0:134 offset1:198
	v_fmac_f32_e32 v107, v106, v105
	s_waitcnt lgkmcnt(0)
	v_mul_f32_e32 v110, v110, v108
	v_fmac_f32_e32 v109, v108, v107
	ds_write_b32 v64, v110
	ds_write_b32 v65, v109 offset:1024
	s_waitcnt lgkmcnt(0)
	s_barrier
	s_and_saveexec_b64 s[42:43], s[40:41]
	s_cbranch_execz .LBB0_387
	ds_read2st64_b32 v[12:13], v64 offset1:1
	ds_read2st64_b32 v[14:15], v64 offset0:2 offset1:3
	s_waitcnt lgkmcnt(1)
	v_mul_f32_e32 v16, v12, v13
	s_waitcnt lgkmcnt(0)
	v_mul_f32_e32 v16, v16, v14
	v_mul_f32_e32 v18, v16, v15
	ds_read2st64_b32 v[16:17], v64 offset0:4 offset1:5
	s_waitcnt lgkmcnt(0)
	v_fma_f32 v12, 0, v12, v16
	v_fmac_f32_e32 v17, v13, v12
	ds_read2st64_b32 v[12:13], v64 offset0:6 offset1:7
	s_waitcnt lgkmcnt(0)
	v_fma_f32 v12, v14, v17, v12
	v_fmac_f32_e32 v13, v15, v12
	global_store_dword v[50:51], v18, off
	global_store_dword v[52:53], v13, off
.LBB0_387:
	s_or_b64 exec, exec, s[42:43]
	v_lshl_add_u64 v[20:21], s[50:51], 0, v[144:145]
	v_lshl_add_u64 v[28:29], v[20:21], 0, v[54:55]
	s_barrier
	s_mov_b32 s5, 0x3e4ccccd
	global_load_dwordx4 v[196:199], v231, s[52:53]
	global_load_dwordx4 v[200:203], v231, s[54:55]
	global_load_dwordx4 v[32:35], v231, s[56:57]
	ds_read_b128 v[12:15], v229 offset:25088
	ds_read_b128 v[16:19], v229 offset:25152
	ds_read_b128 v[28:31], v230 offset:8704
	s_waitcnt lgkmcnt(1)
	v_mfma_f32_16x16x32_bf16 v[20:23], v[232:235], v[12:15], 0
	v_mfma_f32_16x16x32_bf16 v[24:27], v[240:243], v[12:15], 0
	v_mfma_f32_16x16x32_bf16 v[20:23], v[236:239], v[16:19], v[20:23]
	v_mfma_f32_16x16x32_bf16 v[24:27], v[244:247], v[16:19], v[24:27]
	s_waitcnt vmcnt(0)
	s_nop 7
	s_nop 3
	s_waitcnt lgkmcnt(0)
	v_add_f32_e32 v20, v20, v196
	v_add_f32_e32 v21, v21, v197
	v_add_f32_e32 v24, v24, v200
	v_add_f32_e32 v25, v25, v201
	v_mul_f32_e32 v20, 0xbfb8aa3b, v20
	v_mul_f32_e32 v21, 0xbfb8aa3b, v21
	v_mul_f32_e32 v24, 0xbfb8aa3b, v24
	v_mul_f32_e32 v25, 0xbfb8aa3b, v25
	v_exp_f32_e32 v20, v20
	v_exp_f32_e32 v21, v21
	v_exp_f32_e32 v24, v24
	v_exp_f32_e32 v25, v25
	v_add_f32_e32 v20, 1.0, v20
	v_add_f32_e32 v21, 1.0, v21
	v_add_f32_e32 v24, 1.0, v24
	v_add_f32_e32 v25, 1.0, v25
	v_rcp_f32_e32 v20, v20
	v_rcp_f32_e32 v21, v21
	v_rcp_f32_e32 v24, v24
	v_rcp_f32_e32 v25, v25
	v_pk_mul_f32 v[12:13], v[20:21], v[32:33]
	s_nop 0
	v_pk_add_f32 v[14:15], v[12:13], v[12:13]
	v_mul_f32_e32 v20, 0x3fb8aa3b, v12
	v_mul_f32_e32 v21, 0x3fb8aa3b, v13
	v_exp_f32_e32 v20, v20
	v_exp_f32_e32 v21, v21
	v_mul_f32_e32 v16, 0x3e800000, v14
	v_fma_f32 v17, v14, s5, 1.0
	v_mul_f32_e32 v18, 0x3eaaaaab, v14
	v_fma_f32 v16, v16, v17, 1.0
	v_mul_f32_e32 v17, 0.5, v14
	v_fma_f32 v18, v18, v16, 1.0
	v_fma_f32 v17, v17, v18, 1.0
	v_mul_f32_e64 v17, v17, -v14
	v_fma_f32 v16, -v20, v20, 1.0
	v_cmp_lt_f32_e32 vcc, s6, v14
	v_mul_f32_e32 v19, 0x3e800000, v15
	v_fma_f32 v12, v15, s5, 1.0
	v_cndmask_b32_e32 v16, v16, v17, vcc
	v_mul_f32_e32 v13, 0x3eaaaaab, v15
	v_fma_f32 v19, v19, v12, 1.0
	v_mul_f32_e32 v12, 0.5, v15
	v_fma_f32 v13, v13, v19, 1.0
	v_fma_f32 v12, v12, v13, 1.0
	v_mul_f32_e64 v12, v12, -v15
	v_fma_f32 v13, -v21, v21, 1.0
	v_cmp_lt_f32_e32 vcc, s6, v15
	v_sqrt_f32_e32 v16, v16
	s_nop 1
	v_cndmask_b32_e32 v17, v13, v12, vcc
	v_sqrt_f32_e32 v17, v17
	s_nop 0
	v_pk_mul_f32 v[24:25], v[24:25], v[16:17]
	s_nop 0
	v_pk_mul_f32 v[24:25], v[28:29], v[24:25]
	v_add_f32_e32 v22, v22, v198
	v_add_f32_e32 v23, v23, v199
	v_add_f32_e32 v26, v26, v202
	v_add_f32_e32 v27, v27, v203
	v_mul_f32_e32 v22, 0xbfb8aa3b, v22
; __device__ __forceinline__ float sigmoidf_(float x) { return __builtin_amdgcn_rcpf(1.0f + __expf(-x)); }
; template <bool FINAL>
; __device__ void phase_lru(const Params& p, int l, unsigned char* smem) {
;     ...
;       {
;         bf16x8 uf[2];
;         uf[0] = *(const bf16x8*)(ub + (16 * w + l15) * 72 + g * 8);
;         uf[1] = *(const bf16x8*)(ub + (16 * w + l15) * 72 + 32 + g * 8);
;         const int t = 16 * w + l15;
; #pragma unroll
;         for (int et = 0; et < 4; ++et) {
;           f32x4 ar = {0.f, 0.f, 0.f, 0.f}, ai = {0.f, 0.f, 0.f, 0.f};
;           const u16* wr = p.WLRU + ((((size_t)(l * 2 + d) * 2 + 0) * 8 + nb) * 64 + et * 16 + l15) * 64 + g * 8;
;           const u16* wi = p.WLRU + ((((size_t)(l * 2 + d) * 2 + 1) * 8 + nb) * 64 + et * 16 + l15) * 64 + g * 8;
; #pragma unroll
;           for (int ks = 0; ks < 2; ++ks) {
;             ar = mfma16(*(const bf16x8*)(wr + ks * 32), uf[ks], ar);
;             ai = mfma16(*(const bf16x8*)(wi + ks * 32), uf[ks], ai);
;           }
;           const int e0 = et * 16 + 4 * g, ch0 = nb * 64 + e0;
;           const float4 ba4 = *(const float4*)(p.ba + (l * 2 + d) * 512 + ch0);
;           const float4 bx4 = *(const float4*)(p.bx + (l * 2 + d) * 512 + ch0);
;           const float4 sp4 = *(const float4*)(p.SP8 + (l * 2 + d) * 512 + ch0);
;           const float4 uu = *(const float4*)(u32 + t * 64 + e0);
;           const float* bap = (const float*)&ba4; const float* bxp = (const float*)&bx4;
;           const float* spp = (const float*)&sp4; const float* uup = (const float*)&uu;
;           f32x4 av, bv;
; #pragma unroll
;           for (int j = 0; j < 4; ++j) {
;             float r = sigmoidf_(ar[j] + bap[j]);
;             float ig = sigmoidf_(ai[j] + bxp[j]);
;             float la = spp[j] * r;
;             float av_ = __expf(la);
;             float t2 = 2.0f * la;
;             float ser = -t2 * (1.f + t2 * 0.5f * (1.f + t2 * (1.f / 3.f) * (1.f + t2 * 0.25f * (1.f + t2 * 0.2f))));
;             float om = (t2 > -0.25f) ? ser : (1.0f - av_ * av_);
;             av[j] = av_;
;             bv[j] = __builtin_amdgcn_sqrtf(om) * ig * uup[j];
;           }
;           *(f32x4*)(sa + t * 64 + e0) = av;
;           *(f32x4*)(sb + t * 64 + e0) = bv;
;         }
;       }
	v_mul_f32_e32 v23, 0xbfb8aa3b, v23
	v_mul_f32_e32 v26, 0xbfb8aa3b, v26
	v_mul_f32_e32 v27, 0xbfb8aa3b, v27
	v_exp_f32_e32 v22, v22
	v_exp_f32_e32 v23, v23
	v_exp_f32_e32 v26, v26
	v_exp_f32_e32 v27, v27
	v_add_f32_e32 v22, 1.0, v22
	v_add_f32_e32 v23, 1.0, v23
	v_add_f32_e32 v26, 1.0, v26
	v_add_f32_e32 v27, 1.0, v27
	v_rcp_f32_e32 v22, v22
	v_rcp_f32_e32 v23, v23
	v_rcp_f32_e32 v26, v26
	v_rcp_f32_e32 v27, v27
	v_pk_mul_f32 v[12:13], v[22:23], v[34:35]
	s_nop 0
	v_pk_add_f32 v[14:15], v[12:13], v[12:13]
	v_mul_f32_e32 v22, 0x3fb8aa3b, v12
	v_mul_f32_e32 v23, 0x3fb8aa3b, v13
	v_exp_f32_e32 v22, v22
	v_exp_f32_e32 v23, v23
	v_mul_f32_e32 v16, 0x3e800000, v14
	v_fma_f32 v17, v14, s5, 1.0
	v_mul_f32_e32 v18, 0x3eaaaaab, v14
	v_fma_f32 v16, v16, v17, 1.0
	v_mul_f32_e32 v17, 0.5, v14
	v_fma_f32 v18, v18, v16, 1.0
	v_fma_f32 v17, v17, v18, 1.0
	v_mul_f32_e64 v17, v17, -v14
	v_fma_f32 v16, -v22, v22, 1.0
	v_cmp_lt_f32_e32 vcc, s6, v14
	v_mul_f32_e32 v19, 0x3e800000, v15
	v_fma_f32 v12, v15, s5, 1.0
	v_cndmask_b32_e32 v16, v16, v17, vcc
	v_mul_f32_e32 v13, 0x3eaaaaab, v15
	v_fma_f32 v19, v19, v12, 1.0
	v_mul_f32_e32 v12, 0.5, v15
	v_fma_f32 v13, v13, v19, 1.0
	v_fma_f32 v12, v12, v13, 1.0
	v_mul_f32_e64 v12, v12, -v15
	v_fma_f32 v13, -v23, v23, 1.0
	v_cmp_lt_f32_e32 vcc, s6, v15
	v_sqrt_f32_e32 v16, v16
	s_nop 1
	v_cndmask_b32_e32 v17, v13, v12, vcc
	v_sqrt_f32_e32 v17, v17
	s_nop 0
	v_pk_mul_f32 v[26:27], v[26:27], v[16:17]
	s_nop 0
	v_pk_mul_f32 v[26:27], v[30:31], v[26:27]
	ds_write_b128 v230, v[20:23] offset:34304
	ds_write_b128 v230, v[24:27] offset:50688
	ds_read_b128 v[12:15], v229 offset:27392
	ds_read_b128 v[16:19], v229 offset:27456
	ds_read_b128 v[28:31], v230 offset:12800
	s_waitcnt lgkmcnt(1)
	v_mfma_f32_16x16x32_bf16 v[20:23], v[232:235], v[12:15], 0
	v_mfma_f32_16x16x32_bf16 v[24:27], v[240:243], v[12:15], 0
	v_mfma_f32_16x16x32_bf16 v[20:23], v[236:239], v[16:19], v[20:23]
	v_mfma_f32_16x16x32_bf16 v[24:27], v[244:247], v[16:19], v[24:27]
	s_nop 7
	s_nop 3
	s_waitcnt lgkmcnt(0)
	v_add_f32_e32 v20, v20, v196
	v_add_f32_e32 v21, v21, v197
	v_add_f32_e32 v24, v24, v200
	v_add_f32_e32 v25, v25, v201
	v_mul_f32_e32 v20, 0xbfb8aa3b, v20
	v_mul_f32_e32 v21, 0xbfb8aa3b, v21
	v_mul_f32_e32 v24, 0xbfb8aa3b, v24
	v_mul_f32_e32 v25, 0xbfb8aa3b, v25
	v_exp_f32_e32 v20, v20
	v_exp_f32_e32 v21, v21
	v_exp_f32_e32 v24, v24
	v_exp_f32_e32 v25, v25
	v_add_f32_e32 v20, 1.0, v20
	v_add_f32_e32 v21, 1.0, v21
	v_add_f32_e32 v24, 1.0, v24
	v_add_f32_e32 v25, 1.0, v25
	v_rcp_f32_e32 v20, v20
	v_rcp_f32_e32 v21, v21
	v_rcp_f32_e32 v24, v24
	v_rcp_f32_e32 v25, v25
	v_pk_mul_f32 v[12:13], v[20:21], v[32:33]
	s_nop 0
	v_pk_add_f32 v[14:15], v[12:13], v[12:13]
	v_mul_f32_e32 v20, 0x3fb8aa3b, v12
	v_mul_f32_e32 v21, 0x3fb8aa3b, v13
	v_exp_f32_e32 v20, v20
	v_exp_f32_e32 v21, v21
	v_mul_f32_e32 v16, 0x3e800000, v14
	v_fma_f32 v17, v14, s5, 1.0
	v_mul_f32_e32 v18, 0x3eaaaaab, v14
	v_fma_f32 v16, v16, v17, 1.0
	v_mul_f32_e32 v17, 0.5, v14
	v_fma_f32 v18, v18, v16, 1.0
	v_fma_f32 v17, v17, v18, 1.0
	v_mul_f32_e64 v17, v17, -v14
	v_fma_f32 v16, -v20, v20, 1.0
	v_cmp_lt_f32_e32 vcc, s6, v14
	v_mul_f32_e32 v19, 0x3e800000, v15
	v_fma_f32 v12, v15, s5, 1.0
	v_cndmask_b32_e32 v16, v16, v17, vcc
	v_mul_f32_e32 v13, 0x3eaaaaab, v15
	v_fma_f32 v19, v19, v12, 1.0
	v_mul_f32_e32 v12, 0.5, v15
	v_fma_f32 v13, v13, v19, 1.0
	v_fma_f32 v12, v12, v13, 1.0
	v_mul_f32_e64 v12, v12, -v15
	v_fma_f32 v13, -v21, v21, 1.0
	v_cmp_lt_f32_e32 vcc, s6, v15
	v_sqrt_f32_e32 v16, v16
	s_nop 1
	v_cndmask_b32_e32 v17, v13, v12, vcc
	v_sqrt_f32_e32 v17, v17
	s_nop 0
	v_pk_mul_f32 v[24:25], v[24:25], v[16:17]
	s_nop 0
	v_pk_mul_f32 v[24:25], v[28:29], v[24:25]
	v_add_f32_e32 v22, v22, v198
	v_add_f32_e32 v23, v23, v199
	v_add_f32_e32 v26, v26, v202
	v_add_f32_e32 v27, v27, v203
	v_mul_f32_e32 v22, 0xbfb8aa3b, v22
	v_mul_f32_e32 v23, 0xbfb8aa3b, v23
	v_mul_f32_e32 v26, 0xbfb8aa3b, v26
	v_mul_f32_e32 v27, 0xbfb8aa3b, v27
	v_exp_f32_e32 v22, v22
	v_exp_f32_e32 v23, v23
	v_exp_f32_e32 v26, v26
	v_exp_f32_e32 v27, v27
	v_add_f32_e32 v22, 1.0, v22
	v_add_f32_e32 v23, 1.0, v23
	v_add_f32_e32 v26, 1.0, v26
	v_add_f32_e32 v27, 1.0, v27
	v_rcp_f32_e32 v22, v22
	v_rcp_f32_e32 v23, v23
	v_rcp_f32_e32 v26, v26
	v_rcp_f32_e32 v27, v27
	v_pk_mul_f32 v[12:13], v[22:23], v[34:35]
	s_nop 0
	v_pk_add_f32 v[14:15], v[12:13], v[12:13]
	v_mul_f32_e32 v22, 0x3fb8aa3b, v12
	v_mul_f32_e32 v23, 0x3fb8aa3b, v13
	v_exp_f32_e32 v22, v22
	v_exp_f32_e32 v23, v23
	v_mul_f32_e32 v16, 0x3e800000, v14
	v_fma_f32 v17, v14, s5, 1.0
	v_mul_f32_e32 v18, 0x3eaaaaab, v14
	v_fma_f32 v16, v16, v17, 1.0
	v_mul_f32_e32 v17, 0.5, v14
	v_fma_f32 v18, v18, v16, 1.0
	v_fma_f32 v17, v17, v18, 1.0
	v_mul_f32_e64 v17, v17, -v14
	v_fma_f32 v16, -v22, v22, 1.0
	v_cmp_lt_f32_e32 vcc, s6, v14
	v_mul_f32_e32 v19, 0x3e800000, v15
	v_fma_f32 v12, v15, s5, 1.0
	v_cndmask_b32_e32 v16, v16, v17, vcc
	v_mul_f32_e32 v13, 0x3eaaaaab, v15
	v_fma_f32 v19, v19, v12, 1.0
	v_mul_f32_e32 v12, 0.5, v15
	v_fma_f32 v13, v13, v19, 1.0
	v_fma_f32 v12, v12, v13, 1.0
	v_mul_f32_e64 v12, v12, -v15
	v_fma_f32 v13, -v23, v23, 1.0
	v_cmp_lt_f32_e32 vcc, s6, v15
	v_sqrt_f32_e32 v16, v16
	s_nop 1
	v_cndmask_b32_e32 v17, v13, v12, vcc
	v_sqrt_f32_e32 v17, v17
	s_nop 0
	v_pk_mul_f32 v[26:27], v[26:27], v[16:17]
	s_nop 0
	v_pk_mul_f32 v[26:27], v[30:31], v[26:27]
	ds_write_b128 v230, v[20:23] offset:38400
	ds_write_b128 v230, v[24:27] offset:54784
	ds_read_b128 v[12:15], v229 offset:29696
	ds_read_b128 v[16:19], v229 offset:29760
	ds_read_b128 v[28:31], v230 offset:16896
	s_waitcnt lgkmcnt(1)
; __device__ __forceinline__ float sigmoidf_(float x) { return __builtin_amdgcn_rcpf(1.0f + __expf(-x)); }
; template <bool FINAL>
; __device__ void phase_lru(const Params& p, int l, unsigned char* smem) {
;     ...
;       {
;         bf16x8 uf[2];
;         uf[0] = *(const bf16x8*)(ub + (16 * w + l15) * 72 + g * 8);
;         uf[1] = *(const bf16x8*)(ub + (16 * w + l15) * 72 + 32 + g * 8);
;         const int t = 16 * w + l15;
; #pragma unroll
;         for (int et = 0; et < 4; ++et) {
;           f32x4 ar = {0.f, 0.f, 0.f, 0.f}, ai = {0.f, 0.f, 0.f, 0.f};
;           const u16* wr = p.WLRU + ((((size_t)(l * 2 + d) * 2 + 0) * 8 + nb) * 64 + et * 16 + l15) * 64 + g * 8;
;           const u16* wi = p.WLRU + ((((size_t)(l * 2 + d) * 2 + 1) * 8 + nb) * 64 + et * 16 + l15) * 64 + g * 8;
; #pragma unroll
;           for (int ks = 0; ks < 2; ++ks) {
;             ar = mfma16(*(const bf16x8*)(wr + ks * 32), uf[ks], ar);
;             ai = mfma16(*(const bf16x8*)(wi + ks * 32), uf[ks], ai);
;           }
;           const int e0 = et * 16 + 4 * g, ch0 = nb * 64 + e0;
;           const float4 ba4 = *(const float4*)(p.ba + (l * 2 + d) * 512 + ch0);
;           const float4 bx4 = *(const float4*)(p.bx + (l * 2 + d) * 512 + ch0);
;           const float4 sp4 = *(const float4*)(p.SP8 + (l * 2 + d) * 512 + ch0);
;           const float4 uu = *(const float4*)(u32 + t * 64 + e0);
;           const float* bap = (const float*)&ba4; const float* bxp = (const float*)&bx4;
;           const float* spp = (const float*)&sp4; const float* uup = (const float*)&uu;
;           f32x4 av, bv;
; #pragma unroll
;           for (int j = 0; j < 4; ++j) {
;             float r = sigmoidf_(ar[j] + bap[j]);
;             float ig = sigmoidf_(ai[j] + bxp[j]);
;             float la = spp[j] * r;
;             float av_ = __expf(la);
;             float t2 = 2.0f * la;
;             float ser = -t2 * (1.f + t2 * 0.5f * (1.f + t2 * (1.f / 3.f) * (1.f + t2 * 0.25f * (1.f + t2 * 0.2f))));
;             float om = (t2 > -0.25f) ? ser : (1.0f - av_ * av_);
;             av[j] = av_;
;             bv[j] = __builtin_amdgcn_sqrtf(om) * ig * uup[j];
;           }
;           *(f32x4*)(sa + t * 64 + e0) = av;
;           *(f32x4*)(sb + t * 64 + e0) = bv;
;         }
;       }
	v_mfma_f32_16x16x32_bf16 v[20:23], v[232:235], v[12:15], 0
	v_mfma_f32_16x16x32_bf16 v[24:27], v[240:243], v[12:15], 0
	v_mfma_f32_16x16x32_bf16 v[20:23], v[236:239], v[16:19], v[20:23]
	v_mfma_f32_16x16x32_bf16 v[24:27], v[244:247], v[16:19], v[24:27]
	s_nop 7
	s_nop 3
	s_waitcnt lgkmcnt(0)
	v_add_f32_e32 v20, v20, v196
	v_add_f32_e32 v21, v21, v197
	v_add_f32_e32 v24, v24, v200
	v_add_f32_e32 v25, v25, v201
	v_mul_f32_e32 v20, 0xbfb8aa3b, v20
	v_mul_f32_e32 v21, 0xbfb8aa3b, v21
	v_mul_f32_e32 v24, 0xbfb8aa3b, v24
	v_mul_f32_e32 v25, 0xbfb8aa3b, v25
	v_exp_f32_e32 v20, v20
	v_exp_f32_e32 v21, v21
	v_exp_f32_e32 v24, v24
	v_exp_f32_e32 v25, v25
	v_add_f32_e32 v20, 1.0, v20
	v_add_f32_e32 v21, 1.0, v21
	v_add_f32_e32 v24, 1.0, v24
	v_add_f32_e32 v25, 1.0, v25
	v_rcp_f32_e32 v20, v20
	v_rcp_f32_e32 v21, v21
	v_rcp_f32_e32 v24, v24
	v_rcp_f32_e32 v25, v25
	v_pk_mul_f32 v[12:13], v[20:21], v[32:33]
	s_nop 0
	v_pk_add_f32 v[14:15], v[12:13], v[12:13]
	v_mul_f32_e32 v20, 0x3fb8aa3b, v12
	v_mul_f32_e32 v21, 0x3fb8aa3b, v13
	v_exp_f32_e32 v20, v20
	v_exp_f32_e32 v21, v21
	v_mul_f32_e32 v16, 0x3e800000, v14
	v_fma_f32 v17, v14, s5, 1.0
	v_mul_f32_e32 v18, 0x3eaaaaab, v14
	v_fma_f32 v16, v16, v17, 1.0
	v_mul_f32_e32 v17, 0.5, v14
	v_fma_f32 v18, v18, v16, 1.0
	v_fma_f32 v17, v17, v18, 1.0
	v_mul_f32_e64 v17, v17, -v14
	v_fma_f32 v16, -v20, v20, 1.0
	v_cmp_lt_f32_e32 vcc, s6, v14
	v_mul_f32_e32 v19, 0x3e800000, v15
	v_fma_f32 v12, v15, s5, 1.0
	v_cndmask_b32_e32 v16, v16, v17, vcc
	v_mul_f32_e32 v13, 0x3eaaaaab, v15
	v_fma_f32 v19, v19, v12, 1.0
	v_mul_f32_e32 v12, 0.5, v15
	v_fma_f32 v13, v13, v19, 1.0
	v_fma_f32 v12, v12, v13, 1.0
	v_mul_f32_e64 v12, v12, -v15
	v_fma_f32 v13, -v21, v21, 1.0
	v_cmp_lt_f32_e32 vcc, s6, v15
	v_sqrt_f32_e32 v16, v16
	s_nop 1
	v_cndmask_b32_e32 v17, v13, v12, vcc
	v_sqrt_f32_e32 v17, v17
	s_nop 0
	v_pk_mul_f32 v[24:25], v[24:25], v[16:17]
	s_nop 0
	v_pk_mul_f32 v[24:25], v[28:29], v[24:25]
	v_add_f32_e32 v22, v22, v198
	v_add_f32_e32 v23, v23, v199
	v_add_f32_e32 v26, v26, v202
	v_add_f32_e32 v27, v27, v203
	v_mul_f32_e32 v22, 0xbfb8aa3b, v22
	v_mul_f32_e32 v23, 0xbfb8aa3b, v23
	v_mul_f32_e32 v26, 0xbfb8aa3b, v26
	v_mul_f32_e32 v27, 0xbfb8aa3b, v27
	v_exp_f32_e32 v22, v22
	v_exp_f32_e32 v23, v23
	v_exp_f32_e32 v26, v26
	v_exp_f32_e32 v27, v27
	v_add_f32_e32 v22, 1.0, v22
	v_add_f32_e32 v23, 1.0, v23
	v_add_f32_e32 v26, 1.0, v26
	v_add_f32_e32 v27, 1.0, v27
	v_rcp_f32_e32 v22, v22
	v_rcp_f32_e32 v23, v23
	v_rcp_f32_e32 v26, v26
	v_rcp_f32_e32 v27, v27
	v_pk_mul_f32 v[12:13], v[22:23], v[34:35]
	s_nop 0
	v_pk_add_f32 v[14:15], v[12:13], v[12:13]
	v_mul_f32_e32 v22, 0x3fb8aa3b, v12
	v_mul_f32_e32 v23, 0x3fb8aa3b, v13
	v_exp_f32_e32 v22, v22
	v_exp_f32_e32 v23, v23
	v_mul_f32_e32 v16, 0x3e800000, v14
	v_fma_f32 v17, v14, s5, 1.0
	v_mul_f32_e32 v18, 0x3eaaaaab, v14
	v_fma_f32 v16, v16, v17, 1.0
	v_mul_f32_e32 v17, 0.5, v14
	v_fma_f32 v18, v18, v16, 1.0
	v_fma_f32 v17, v17, v18, 1.0
	v_mul_f32_e64 v17, v17, -v14
	v_fma_f32 v16, -v22, v22, 1.0
	v_cmp_lt_f32_e32 vcc, s6, v14
	v_mul_f32_e32 v19, 0x3e800000, v15
	v_fma_f32 v12, v15, s5, 1.0
	v_cndmask_b32_e32 v16, v16, v17, vcc
	v_mul_f32_e32 v13, 0x3eaaaaab, v15
	v_fma_f32 v19, v19, v12, 1.0
	v_mul_f32_e32 v12, 0.5, v15
	v_fma_f32 v13, v13, v19, 1.0
	v_fma_f32 v12, v12, v13, 1.0
	v_mul_f32_e64 v12, v12, -v15
	v_fma_f32 v13, -v23, v23, 1.0
	v_cmp_lt_f32_e32 vcc, s6, v15
	v_sqrt_f32_e32 v16, v16
	s_nop 1
	v_cndmask_b32_e32 v17, v13, v12, vcc
	v_sqrt_f32_e32 v17, v17
	s_nop 0
	v_pk_mul_f32 v[26:27], v[26:27], v[16:17]
	s_nop 0
	v_pk_mul_f32 v[26:27], v[30:31], v[26:27]
	ds_write_b128 v230, v[20:23] offset:42496
	ds_write_b128 v230, v[24:27] offset:58880
	ds_read_b128 v[12:15], v229 offset:32000
	ds_read_b128 v[16:19], v229 offset:32064
	ds_read_b128 v[28:31], v230 offset:20992
	s_waitcnt lgkmcnt(1)
	v_mfma_f32_16x16x32_bf16 v[20:23], v[232:235], v[12:15], 0
	v_mfma_f32_16x16x32_bf16 v[24:27], v[240:243], v[12:15], 0
	v_mfma_f32_16x16x32_bf16 v[20:23], v[236:239], v[16:19], v[20:23]
	v_mfma_f32_16x16x32_bf16 v[24:27], v[244:247], v[16:19], v[24:27]
	s_nop 7
	s_nop 3
	s_waitcnt lgkmcnt(0)
; __device__ __forceinline__ float sigmoidf_(float x) { return __builtin_amdgcn_rcpf(1.0f + __expf(-x)); }
; template <bool FINAL>
; __device__ void phase_lru(const Params& p, int l, unsigned char* smem) {
;     ...
;       {
;         bf16x8 uf[2];
;         uf[0] = *(const bf16x8*)(ub + (16 * w + l15) * 72 + g * 8);
;         uf[1] = *(const bf16x8*)(ub + (16 * w + l15) * 72 + 32 + g * 8);
;         const int t = 16 * w + l15;
; #pragma unroll
;         for (int et = 0; et < 4; ++et) {
;           f32x4 ar = {0.f, 0.f, 0.f, 0.f}, ai = {0.f, 0.f, 0.f, 0.f};
;           const u16* wr = p.WLRU + ((((size_t)(l * 2 + d) * 2 + 0) * 8 + nb) * 64 + et * 16 + l15) * 64 + g * 8;
;           const u16* wi = p.WLRU + ((((size_t)(l * 2 + d) * 2 + 1) * 8 + nb) * 64 + et * 16 + l15) * 64 + g * 8;
; #pragma unroll
;           for (int ks = 0; ks < 2; ++ks) {
;             ar = mfma16(*(const bf16x8*)(wr + ks * 32), uf[ks], ar);
;             ai = mfma16(*(const bf16x8*)(wi + ks * 32), uf[ks], ai);
;           }
;           const int e0 = et * 16 + 4 * g, ch0 = nb * 64 + e0;
;           const float4 ba4 = *(const float4*)(p.ba + (l * 2 + d) * 512 + ch0);
;           const float4 bx4 = *(const float4*)(p.bx + (l * 2 + d) * 512 + ch0);
;           const float4 sp4 = *(const float4*)(p.SP8 + (l * 2 + d) * 512 + ch0);
;           const float4 uu = *(const float4*)(u32 + t * 64 + e0);
;           const float* bap = (const float*)&ba4; const float* bxp = (const float*)&bx4;
;           const float* spp = (const float*)&sp4; const float* uup = (const float*)&uu;
;           f32x4 av, bv;
; #pragma unroll
;           for (int j = 0; j < 4; ++j) {
;             float r = sigmoidf_(ar[j] + bap[j]);
;             float ig = sigmoidf_(ai[j] + bxp[j]);
;             float la = spp[j] * r;
;             float av_ = __expf(la);
;             float t2 = 2.0f * la;
;             float ser = -t2 * (1.f + t2 * 0.5f * (1.f + t2 * (1.f / 3.f) * (1.f + t2 * 0.25f * (1.f + t2 * 0.2f))));
;             float om = (t2 > -0.25f) ? ser : (1.0f - av_ * av_);
;             av[j] = av_;
;             bv[j] = __builtin_amdgcn_sqrtf(om) * ig * uup[j];
;           }
;           *(f32x4*)(sa + t * 64 + e0) = av;
;           *(f32x4*)(sb + t * 64 + e0) = bv;
;         }
;       }
;       __syncthreads();
;       {
;         float A = 1.f, B = 0.f;
;         if (d == 0) {
; #pragma unroll
	v_add_f32_e32 v20, v20, v196
	v_add_f32_e32 v21, v21, v197
	v_add_f32_e32 v24, v24, v200
	v_add_f32_e32 v25, v25, v201
	v_mul_f32_e32 v20, 0xbfb8aa3b, v20
	v_mul_f32_e32 v21, 0xbfb8aa3b, v21
	v_mul_f32_e32 v24, 0xbfb8aa3b, v24
	v_mul_f32_e32 v25, 0xbfb8aa3b, v25
	v_exp_f32_e32 v20, v20
	v_exp_f32_e32 v21, v21
	v_exp_f32_e32 v24, v24
	v_exp_f32_e32 v25, v25
	v_add_f32_e32 v20, 1.0, v20
	v_add_f32_e32 v21, 1.0, v21
	v_add_f32_e32 v24, 1.0, v24
	v_add_f32_e32 v25, 1.0, v25
	v_rcp_f32_e32 v20, v20
	v_rcp_f32_e32 v21, v21
	v_rcp_f32_e32 v24, v24
	v_rcp_f32_e32 v25, v25
	v_pk_mul_f32 v[12:13], v[20:21], v[32:33]
	s_nop 0
	v_pk_add_f32 v[14:15], v[12:13], v[12:13]
	v_mul_f32_e32 v20, 0x3fb8aa3b, v12
	v_mul_f32_e32 v21, 0x3fb8aa3b, v13
	v_exp_f32_e32 v20, v20
	v_exp_f32_e32 v21, v21
	v_mul_f32_e32 v16, 0x3e800000, v14
	v_fma_f32 v17, v14, s5, 1.0
	v_mul_f32_e32 v18, 0x3eaaaaab, v14
	v_fma_f32 v16, v16, v17, 1.0
	v_mul_f32_e32 v17, 0.5, v14
	v_fma_f32 v18, v18, v16, 1.0
	v_fma_f32 v17, v17, v18, 1.0
	v_mul_f32_e64 v17, v17, -v14
	v_fma_f32 v16, -v20, v20, 1.0
	v_cmp_lt_f32_e32 vcc, s6, v14
	v_mul_f32_e32 v19, 0x3e800000, v15
	v_fma_f32 v12, v15, s5, 1.0
	v_cndmask_b32_e32 v16, v16, v17, vcc
	v_mul_f32_e32 v13, 0x3eaaaaab, v15
	v_fma_f32 v19, v19, v12, 1.0
	v_mul_f32_e32 v12, 0.5, v15
	v_fma_f32 v13, v13, v19, 1.0
	v_fma_f32 v12, v12, v13, 1.0
	v_mul_f32_e64 v12, v12, -v15
	v_fma_f32 v13, -v21, v21, 1.0
	v_cmp_lt_f32_e32 vcc, s6, v15
	v_sqrt_f32_e32 v16, v16
	s_nop 1
	v_cndmask_b32_e32 v17, v13, v12, vcc
	v_sqrt_f32_e32 v17, v17
	s_nop 0
	v_pk_mul_f32 v[24:25], v[24:25], v[16:17]
	s_nop 0
	v_pk_mul_f32 v[24:25], v[28:29], v[24:25]
	v_add_f32_e32 v22, v22, v198
	v_add_f32_e32 v23, v23, v199
	v_add_f32_e32 v26, v26, v202
	v_add_f32_e32 v27, v27, v203
	v_mul_f32_e32 v22, 0xbfb8aa3b, v22
	v_mul_f32_e32 v23, 0xbfb8aa3b, v23
	v_mul_f32_e32 v26, 0xbfb8aa3b, v26
	v_mul_f32_e32 v27, 0xbfb8aa3b, v27
	v_exp_f32_e32 v22, v22
	v_exp_f32_e32 v23, v23
	v_exp_f32_e32 v26, v26
	v_exp_f32_e32 v27, v27
	v_add_f32_e32 v22, 1.0, v22
	v_add_f32_e32 v23, 1.0, v23
	v_add_f32_e32 v26, 1.0, v26
	v_add_f32_e32 v27, 1.0, v27
	v_rcp_f32_e32 v22, v22
	v_rcp_f32_e32 v23, v23
	v_rcp_f32_e32 v26, v26
	v_rcp_f32_e32 v27, v27
	v_pk_mul_f32 v[12:13], v[22:23], v[34:35]
	s_nop 0
	v_pk_add_f32 v[14:15], v[12:13], v[12:13]
	v_mul_f32_e32 v22, 0x3fb8aa3b, v12
	v_mul_f32_e32 v23, 0x3fb8aa3b, v13
	v_exp_f32_e32 v22, v22
	v_exp_f32_e32 v23, v23
	v_mul_f32_e32 v16, 0x3e800000, v14
	v_fma_f32 v17, v14, s5, 1.0
	v_mul_f32_e32 v18, 0x3eaaaaab, v14
	v_fma_f32 v16, v16, v17, 1.0
	v_mul_f32_e32 v17, 0.5, v14
	v_fma_f32 v18, v18, v16, 1.0
	v_fma_f32 v17, v17, v18, 1.0
	v_mul_f32_e64 v17, v17, -v14
	v_fma_f32 v16, -v22, v22, 1.0
	v_cmp_lt_f32_e32 vcc, s6, v14
	v_mul_f32_e32 v19, 0x3e800000, v15
	v_fma_f32 v12, v15, s5, 1.0
	v_cndmask_b32_e32 v16, v16, v17, vcc
	v_mul_f32_e32 v13, 0x3eaaaaab, v15
	v_fma_f32 v19, v19, v12, 1.0
	v_mul_f32_e32 v12, 0.5, v15
	v_fma_f32 v13, v13, v19, 1.0
	v_fma_f32 v12, v12, v13, 1.0
	v_mul_f32_e64 v12, v12, -v15
	v_fma_f32 v13, -v23, v23, 1.0
	v_cmp_lt_f32_e32 vcc, s6, v15
	v_sqrt_f32_e32 v16, v16
	s_nop 1
	v_cndmask_b32_e32 v17, v13, v12, vcc
	v_sqrt_f32_e32 v17, v17
	s_nop 0
	v_pk_mul_f32 v[26:27], v[26:27], v[16:17]
	s_nop 0
	v_pk_mul_f32 v[26:27], v[30:31], v[26:27]
	ds_write_b128 v230, v[20:23] offset:46592
	ds_write_b128 v230, v[24:27] offset:62976
	s_waitcnt lgkmcnt(0)
	s_barrier
	ds_read2st64_b32 v[12:13], v96 offset0:134 offset1:198
	ds_read2st64_b32 v[14:15], v95 offset0:134 offset1:198
	ds_read2st64_b32 v[16:17], v94 offset0:134 offset1:198
	ds_read2st64_b32 v[104:105], v83 offset0:134 offset1:198
	ds_read2st64_b32 v[106:107], v82 offset0:134 offset1:198
	s_waitcnt lgkmcnt(4)
	v_fmac_f32_e32 v13, 0, v12
	s_waitcnt lgkmcnt(3)
	v_mul_f32_e32 v18, v12, v14
	s_waitcnt lgkmcnt(2)
	v_mul_f32_e32 v20, v18, v16
	ds_read2st64_b32 v[18:19], v93 offset0:134 offset1:198
	v_fmac_f32_e32 v15, v14, v13
	v_fmac_f32_e32 v17, v16, v15
	ds_read2st64_b32 v[108:109], v49 offset0:134 offset1:198
	s_waitcnt lgkmcnt(1)
	v_mul_f32_e32 v22, v20, v18
	ds_read2st64_b32 v[20:21], v92 offset0:134 offset1:198
	v_fmac_f32_e32 v19, v18, v17
	s_waitcnt lgkmcnt(0)
	v_mul_f32_e32 v24, v22, v20
	ds_read2st64_b32 v[22:23], v91 offset0:134 offset1:198
	v_fmac_f32_e32 v21, v20, v19
	s_waitcnt lgkmcnt(0)
	v_mul_f32_e32 v26, v24, v22
	ds_read2st64_b32 v[24:25], v90 offset0:134 offset1:198
	v_fmac_f32_e32 v23, v22, v21
	s_waitcnt lgkmcnt(0)
	v_mul_f32_e32 v28, v26, v24
	ds_read2st64_b32 v[26:27], v89 offset0:134 offset1:198
	v_fmac_f32_e32 v25, v24, v23
	s_waitcnt lgkmcnt(0)
	v_mul_f32_e32 v30, v28, v26
	ds_read2st64_b32 v[28:29], v88 offset0:134 offset1:198
	v_fmac_f32_e32 v27, v26, v25
	s_waitcnt lgkmcnt(0)
	v_mul_f32_e32 v32, v30, v28
	ds_read2st64_b32 v[30:31], v87 offset0:134 offset1:198
	v_fmac_f32_e32 v29, v28, v27
	s_waitcnt lgkmcnt(0)
	v_mul_f32_e32 v34, v32, v30
	ds_read2st64_b32 v[32:33], v86 offset0:134 offset1:198
	v_fmac_f32_e32 v31, v30, v29
	s_waitcnt lgkmcnt(0)
	v_mul_f32_e32 v54, v34, v32
	ds_read2st64_b32 v[34:35], v85 offset0:134 offset1:198
	v_fmac_f32_e32 v33, v32, v31
	s_waitcnt lgkmcnt(0)
	v_mul_f32_e32 v56, v54, v34
	ds_read2st64_b32 v[54:55], v84 offset0:134 offset1:198
	v_fmac_f32_e32 v35, v34, v33
	s_waitcnt lgkmcnt(0)
	v_mul_f32_e32 v56, v56, v54
	v_mul_f32_e32 v56, v56, v104
	v_fmac_f32_e32 v55, v54, v35
	v_mul_f32_e32 v56, v56, v106
	v_fmac_f32_e32 v105, v104, v55
	v_mul_f32_e32 v56, v56, v108
	v_fmac_f32_e32 v107, v106, v105
	v_fmac_f32_e32 v109, v108, v107
	ds_write_b32 v64, v56
	ds_write_b32 v65, v109 offset:1024
	s_waitcnt lgkmcnt(0)
	s_barrier
	s_and_saveexec_b64 s[42:43], s[40:41]
	s_cbranch_execz .LBB0_374
	ds_read2st64_b32 v[12:13], v64 offset0:2 offset1:3
	ds_read2st64_b32 v[14:15], v64 offset1:1
	ds_read_b32 v17, v97
	s_waitcnt lgkmcnt(2)
	v_mul_f32_e32 v16, v13, v12
	s_waitcnt lgkmcnt(1)
	v_mul_f32_e32 v16, v16, v15
	s_waitcnt lgkmcnt(0)
	v_fmac_f32_e32 v17, 0, v13
	ds_read_b32 v13, v98
	v_mul_f32_e32 v16, v16, v14
	s_waitcnt lgkmcnt(0)
	v_fmac_f32_e32 v13, v12, v17
	ds_read_b32 v12, v99
	s_waitcnt lgkmcnt(0)
	v_fmac_f32_e32 v12, v15, v13
	ds_read_b32 v13, v100
	s_waitcnt lgkmcnt(0)
	v_fmac_f32_e32 v13, v14, v12
	global_store_dword v[50:51], v16, off offset:2048
	global_store_dword v[52:53], v13, off offset:2048
	s_branch .LBB0_374
